# rwkv tiles: next-chunk stash and the prefetch for the chunk after it moved to the middle of the scan (a full chunk period of latency cover); DUAL loop-tail barrier no longer drains vmcnt
# baseline (speedup 1.0000x reference)
; __device__ __forceinline__ int launder(int x) { asm volatile("" : "+v"(x)); return x; }
; template <bool DUAL>
; __device__ __forceinline__ void rwkv_tile(const Params& p, int l, int tile, unsigned char* smem) {
;     ...
;   const int tid = launder(threadIdx.x), lane = tid & 63, w = tid >> 6, fr = lane & 15, fq = lane >> 4;
;   const int row = rg * 16 + w * 4 + fq;
;   const int c0 = fr * 4;
;   const int ld2 = l * 2 + d;
;   const size_t rowbase = (size_t)b * TPB;
;   const int lc = (tid & 15) * 4;
;   const float* mu0 = p.rwkv_mu + (size_t)(l * 2 + 0) * 1024 + h * 64 + lc;
;   const float* mu1 = p.rwkv_mu + (size_t)(l * 2 + 1) * 1024 + h * 64 + lc;
;   const float4 m0r = *(const float4*)mu0, m1r = *(const float4*)mu1;
;   const float4 m0k = *(const float4*)(mu0 + 256), m1k = *(const float4*)(mu1 + 256);
;   const float4 m0v = *(const float4*)(mu0 + 512), m1v = *(const float4*)(mu1 + 512);
;   const float4 ka4 = *(const float4*)(p.rwkv_k_a + ld2 * 256 + h * 64 + lc);
;   v2f sA = {0.f, 0.f}, sB = {0.f, 0.f};
;   v2f iA = {(row == c0) ? 1.f : 0.f, (row == c0 + 1) ? 1.f : 0.f}, iB = {(row == c0 + 2) ? 1.f : 0.f, (row == c0 + 3) ? 1.f : 0.f};
;   const int pcc = tid % 24, prow = tid / 24;
;   const bool pact = tid < 240;
;   const bf16_t* rbase_g = p.PR + rowbase * 1024 + (pcc >> 3) * 256 + h * 64 + (pcc & 7) * 8;
;   const bf16_t* pbase_g = p.PRE + (size_t)(pcc >> 3) * PRE_ARR + (rowbase * 2 + d) * 256 + h * 64 + (pcc & 7) * 8;
;   uint4 pf0, pf1, pf2, pf3, pg0, pg1, pg2, pg3;
;     ...
;   RW_PREFETCH(cbeg);
;   RW_STASH();
;   __syncthreads();
.LBB0_1409:
	s_or_b64 exec, exec, s[48:49]
	v_and_b32_e32 v101, 15, v61
	v_bfe_u32 v68, v61, 4, 2
	v_ashrrev_i32_e32 v61, 4, v61
	v_and_b32_e32 v66, -4, v61
	v_readlane_b32 s0, v253, 62
	v_lshlrev_b32_e32 v67, 2, v101
	v_lshl_add_u32 v62, v62, 1, 0
	v_add_u32_e32 v69, s0, v66
	v_or_b32_e32 v66, v69, v68
	v_cmp_eq_u32_e32 vcc, v66, v67
	v_or_b32_e32 v70, 1, v67
	v_lshl_add_u32 v105, v64, 1, v62
	v_lshl_add_u32 v106, v65, 1, v62
	v_add_u32_e32 v64, 1, v61
	v_sub_u32_e32 v65, 32, v61
	v_cndmask_b32_e64 v88, 0, 1.0, vcc
	v_cmp_eq_u32_e32 vcc, v66, v70
	v_or_b32_e32 v70, 2, v67
	v_lshlrev_b32_e32 v60, 1, v60
	s_movk_i32 s0, 0x180
	v_cndmask_b32_e64 v64, v65, v64, s[36:37]
	v_cndmask_b32_e64 v89, 0, 1.0, vcc
	v_cmp_eq_u32_e32 vcc, v66, v70
	v_add_u32_e32 v70, 0, v60
	v_mul_lo_u32 v64, v64, s0
	s_movk_i32 s1, 0x600
	v_add_u32_e32 v107, v70, v64
	v_add3_u32 v111, 0, v64, v60
	v_mul_lo_u32 v64, v61, s1
	v_add_u32_e32 v65, 17, v61
	v_sub_u32_e32 v61, 16, v61
	v_or_b32_e32 v67, 3, v67
	v_cndmask_b32_e64 v61, v61, v65, s[36:37]
	v_cndmask_b32_e64 v90, 0, 1.0, vcc
	v_cmp_eq_u32_e32 vcc, v66, v67
	v_ashrrev_i32_e32 v67, 31, v66
	v_lshl_add_u32 v104, v63, 1, v62
	v_mul_lo_u32 v63, v100, s0
	v_mul_lo_u32 v61, v61, s0
	v_readlane_b32 s0, v254, 21
	v_add_u32_e32 v71, v70, v60
	v_add_u32_e32 v112, v70, v61
	v_add3_u32 v116, 0, v61, v60
	v_lshlrev_b64 v[60:61], 1, v[66:67]
	v_readlane_b32 s1, v254, 22
	v_lshlrev_b32_e32 v72, 4, v101
	v_mov_b32_e32 v165, v164
	v_lshl_add_u64 v[84:85], s[0:1], 0, v[60:61]
	v_readlane_b32 s0, v254, 23
	v_readlane_b32 s1, v254, 24
	v_cndmask_b32_e64 v91, 0, 1.0, vcc
	v_add_u32_e32 v102, 0, v72
	v_lshl_add_u64 v[86:87], s[0:1], 0, v[60:61]
	v_add_u32_e32 v60, v69, v68
	v_readlane_b32 s0, v255, 26
	v_lshl_add_u32 v103, v66, 2, 0
	v_add_u32_e32 v108, 0xfffffe80, v107
	v_lshl_add_u32 v117, v60, 2, s0
	v_readlane_b32 s0, v255, 27
	v_add_u32_e32 v109, 0xffffff00, v107
	v_add_u32_e32 v110, 0xffffff80, v107
	v_add_u32_e32 v113, 0xfffffe80, v112
	v_add_u32_e32 v114, 0xffffff00, v112
	v_add_u32_e32 v115, 0xffffff80, v112
	v_add_u32_e32 v118, s0, v72
	s_movk_i32 s28, 0x58
	v_add_u32_e32 v119, v71, v64
	v_add_u32_e32 v120, v62, v63
	v_mov_b64_e32 v[94:95], v[164:165]
	v_mov_b64_e32 v[92:93], v[164:165]
	s_waitcnt vmcnt(0) lgkmcnt(0)
	s_barrier
	s_branch .LBB0_1411

.LBB0_1411:
	s_add_i32 s52, s28, 1
	s_cmpk_eq_i32 s28, 0x87
	s_cbranch_scc1 .Lrw_du_nopf
	s_cmpk_eq_u32 s28, 0x58
	s_cbranch_scc1 .Lrw_du_dotop
	s_cmpk_lg_u32 s52, 0x87
	s_cbranch_scc1 .Lrw_du_nopf
.Lrw_du_dotop:
	s_lshl_b32 s53, s52, 5
	s_sub_i32 s54, 0x11e0, s53
	s_and_b64 s[50:51], s[36:37], exec
	s_cselect_b32 s53, s53, s54
	s_add_i32 s54, s53, -1
	s_cmpk_eq_u32 s52, 0x87
	s_cbranch_scc1 .Lrw_du_pfslow
	s_and_saveexec_b64 s[50:51], s[42:43]
	v_add_u32_e32 v32, s54, v97
	v_lshlrev_b32_e32 v32, 11, v32
	v_mov_b32_e32 v33, v164
	v_lshl_add_u64 v[32:33], v[80:81], 0, v[32:33]
	global_load_dwordx4 v[32:35], v[32:33], off
	v_add_u32_e32 v28, s54, v98
	v_lshlrev_b32_e32 v28, 11, v28
	v_mov_b32_e32 v29, v164
	v_lshl_add_u64 v[28:29], v[80:81], 0, v[28:29]
	global_load_dwordx4 v[28:31], v[28:29], off
	v_add_u32_e32 v36, s54, v99
	v_lshlrev_b32_e32 v36, 11, v36
	v_mov_b32_e32 v37, v164
	v_lshl_add_u64 v[36:37], v[80:81], 0, v[36:37]
	global_load_dwordx4 v[36:39], v[36:37], off
	v_add_u32_e32 v44, s53, v97
	v_mov_b32_e32 v45, v164
	v_lshlrev_b64 v[44:45], 10, v[44:45]
	v_lshl_add_u64 v[44:45], v[82:83], 0, v[44:45]
	global_load_dwordx4 v[44:47], v[44:45], off
	v_add_u32_e32 v48, s53, v98
	v_mov_b32_e32 v49, v164
	v_lshlrev_b64 v[48:49], 10, v[48:49]
	v_lshl_add_u64 v[48:49], v[82:83], 0, v[48:49]
	global_load_dwordx4 v[48:51], v[48:49], off
	v_add_u32_e32 v52, s53, v99
	v_mov_b32_e32 v53, v164
	v_lshlrev_b64 v[52:53], 10, v[52:53]
	v_lshl_add_u64 v[52:53], v[82:83], 0, v[52:53]
	global_load_dwordx4 v[52:55], v[52:53], off
	s_mov_b64 exec, s[50:51]
	s_and_b64 exec, exec, s[44:45]
	v_add_u32_e32 v40, s54, v100
	v_lshlrev_b32_e32 v40, 11, v40
	v_mov_b32_e32 v41, v164
	v_lshl_add_u64 v[40:41], v[80:81], 0, v[40:41]
	global_load_dwordx4 v[40:43], v[40:41], off
	s_mov_b64 exec, s[50:51]
	s_and_b64 exec, exec, s[46:47]
	v_add_u32_e32 v56, s53, v100
	v_mov_b32_e32 v57, v164
	v_lshlrev_b64 v[56:57], 10, v[56:57]
	v_lshl_add_u64 v[56:57], v[82:83], 0, v[56:57]
	global_load_dwordx4 v[56:59], v[56:57], off
	s_mov_b64 exec, s[50:51]
	s_branch .Lrw_du_nopf

.LBB0_1468:
	s_add_i32 s56, s28, 1
	v_readlane_b32 s0, v254, 14
	s_cmp_ge_u32 s56, s0
	s_cbranch_scc1 .Lrw_nd_nopf
	v_readlane_b32 s0, v254, 17
	s_cmp_eq_u32 s28, s0
	s_cbranch_scc1 .Lrw_nd_dotop
	s_cmp_eq_u32 s56, 7
	s_cbranch_scc1 .Lrw_nd_dotop
	s_cmp_eq_u32 s56, 8
	s_cbranch_scc1 .Lrw_nd_dotop
	s_cmpk_lg_u32 s56, 0x87
	s_cbranch_scc1 .Lrw_nd_nopf
.Lrw_nd_dotop:
	s_lshl_b32 s57, s56, 5
	s_sub_i32 s58, 0xe0, s57
	s_and_b64 s[50:51], s[36:37], exec
	s_cselect_b32 s64, s57, s58
	s_sub_i32 s58, 0x11e0, s57
	s_and_b64 s[50:51], s[36:37], exec
	s_cselect_b32 s50, s57, s58
	s_cmp_lt_u32 s28, 7
	s_movk_i32 s0, 0x10ff
	s_cselect_b32 s57, s64, s50
	s_cselect_b32 s58, 0xff, s0
	s_cselect_b32 s59, 0, 0x100
	s_add_i32 s66, s57, -1
	s_cmp_eq_u32 s56, 7
	s_cbranch_scc1 .Lrw_nd_pfslow
	s_cmp_eq_u32 s56, 8
	s_cbranch_scc1 .Lrw_nd_pfslow
	s_cmpk_eq_u32 s56, 0x87
	s_cbranch_scc1 .Lrw_nd_pfslow
	s_and_saveexec_b64 s[50:51], s[42:43]
	v_add_u32_e32 v32, s66, v93
	v_lshlrev_b32_e32 v32, 11, v32
	v_mov_b32_e32 v33, v164
	v_lshl_add_u64 v[32:33], v[84:85], 0, v[32:33]
	global_load_dwordx4 v[32:35], v[32:33], off
	v_add_u32_e32 v28, s66, v94
	v_lshlrev_b32_e32 v28, 11, v28
	v_mov_b32_e32 v29, v164
	v_lshl_add_u64 v[28:29], v[84:85], 0, v[28:29]
	global_load_dwordx4 v[28:31], v[28:29], off
	v_add_u32_e32 v36, s66, v95
	v_lshlrev_b32_e32 v36, 11, v36
	v_mov_b32_e32 v37, v164
	v_lshl_add_u64 v[36:37], v[84:85], 0, v[36:37]
	global_load_dwordx4 v[36:39], v[36:37], off
	v_add_u32_e32 v44, s57, v93
	v_mov_b32_e32 v45, v164
	v_lshlrev_b64 v[44:45], 10, v[44:45]
	v_lshl_add_u64 v[44:45], v[86:87], 0, v[44:45]
	global_load_dwordx4 v[44:47], v[44:45], off
	v_add_u32_e32 v48, s57, v94
	v_mov_b32_e32 v49, v164
	v_lshlrev_b64 v[48:49], 10, v[48:49]
	v_lshl_add_u64 v[48:49], v[86:87], 0, v[48:49]
	global_load_dwordx4 v[48:51], v[48:49], off
	v_add_u32_e32 v52, s57, v95
	v_mov_b32_e32 v53, v164
	v_lshlrev_b64 v[52:53], 10, v[52:53]
	v_lshl_add_u64 v[52:53], v[86:87], 0, v[52:53]
	global_load_dwordx4 v[52:55], v[52:53], off
	s_mov_b64 exec, s[50:51]
	s_andn2_b64 exec, exec, s[46:47]
	v_add_u32_e32 v40, s66, v96
	v_lshlrev_b32_e32 v40, 11, v40
	v_mov_b32_e32 v41, v164
	v_lshl_add_u64 v[40:41], v[84:85], 0, v[40:41]
	global_load_dwordx4 v[40:43], v[40:41], off
	s_mov_b64 exec, s[50:51]
	s_and_b64 exec, exec, s[48:49]
	v_add_u32_e32 v56, s57, v96
	v_mov_b32_e32 v57, v164
	v_lshlrev_b64 v[56:57], 10, v[56:57]
	v_lshl_add_u64 v[56:57], v[86:87], 0, v[56:57]
	global_load_dwordx4 v[56:59], v[56:57], off
	s_mov_b64 exec, s[50:51]
	s_branch .Lrw_nd_nopf

; template <bool DUAL>
; __device__ __forceinline__ void rwkv_tile(const Params& p, int l, int tile, unsigned char* smem) {
;     ...
;     if (cix + 1 < cend) RW_STASH();
;     __syncthreads();
;   }
.Lrw_nd_b2:
	s_and_b64 vcc, exec, s[52:53]
	s_waitcnt lgkmcnt(0)
	s_barrier
	s_cbranch_vccnz .LBB0_1498
	s_mov_b32 s28, s56
	s_branch .LBB0_1468

; template <bool DUAL>
; __device__ __forceinline__ void rwkv_tile(const Params& p, int l, int tile, unsigned char* smem) {
;     ...
;       for (int i = 0; i < 32; ++i) {
;         const int inx = (i + 1) & 31;
;         const float4 nw4 = *(const float4*)(rp + inx * 384), nkk4 = *(const float4*)(rp + inx * 384 + 64), nkb4 = *(const float4*)(rp + inx * 384 + 128);
;         const float4 nkd4 = *(const float4*)(rp + inx * 384 + 192), nr4 = *(const float4*)(rp + inx * 384 + 256);
;         const float nv = vp[inx * 384];
;         v2f t = sA * (v2f){kk4.x, kk4.y};
;         t = sB * (v2f){kk4.z, kk4.w} + t;
;         float sa = t.x + t.y, ia = 0.f;
;         if (DUAL) {
;           v2f ti = iA * (v2f){kk4.x, kk4.y};
;           ti = iB * (v2f){kk4.z, kk4.w} + ti;
;           ia = ti.x + ti.y;
;           sa += dppf<0xB1>(sa); ia += dppf<0xB1>(ia);
;           sa += dppf<0x4E>(sa); ia += dppf<0x4E>(ia);
;           sa += dppf<0x141>(sa); ia += dppf<0x141>(ia);
;           sa += dppf<0x140>(sa); ia += dppf<0x140>(ia);
;         } else {
;           sa = sum16(sa);
;         }
;         v2f cA = sA * (v2f){w4.x, w4.y} + (v2f){kd4.x, kd4.y} * v;
;         v2f cB = sB * (v2f){w4.z, w4.w} + (v2f){kd4.z, kd4.w} * v;
;         sA = cA - (v2f){kb4.x, kb4.y} * sa;
;         sB = cB - (v2f){kb4.z, kb4.w} * sa;
;         v2f u = sA * (v2f){r4.x, r4.y};
;         u = sB * (v2f){r4.z, r4.w} + u;
;         float y = u.x + u.y, g = 0.f;
;         if (DUAL) {
;           iA = iA * (v2f){w4.x, w4.y} - (v2f){kb4.x, kb4.y} * ia;
;           iB = iB * (v2f){w4.z, w4.w} - (v2f){kb4.z, kb4.w} * ia;
;           v2f ui = iA * (v2f){r4.x, r4.y};
;           ui = iB * (v2f){r4.z, r4.w} + ui;
;           g = ui.x + ui.y;
;           y += dppf<0xB1>(y); g += dppf<0xB1>(g);
;           y += dppf<0x4E>(y); g += dppf<0x4E>(g);
;           y += dppf<0x141>(y); g += dppf<0x141>(g);
;           y += dppf<0x140>(y); g += dppf<0x140>(g);
;           if (fr == (i & 15)) gkeep = g;
;         } else {
;           y = sum16(y);
;         }
;         if (fr == (i & 15)) ykeep = y;
;         if ((i & 15) == 15) {
;           const int ii = (i & 16) + fr;
;           const int ri = (d == 0) ? ii + 1 : 32 - ii;
;           const int pi = plo - 1 + ri;
;           p.yR[((size_t)d * TOK + rowbase + pi) * 256 + h * 64 + row] = f2bf(ykeep);
.Lrw_du_loop:
	s_waitcnt lgkmcnt(6)
	v_pk_mul_f32 v[60:61], v[94:95], v[220:221]
	v_pk_mul_f32 v[62:63], v[88:89], v[220:221]
	v_pk_fma_f32 v[60:61], v[92:93], v[222:223], v[60:61]
	v_pk_fma_f32 v[62:63], v[90:91], v[222:223], v[62:63]
	v_add_f32_e32 v60, v60, v61
	v_add_f32_e32 v62, v62, v63
	v_pk_mul_f32 v[94:95], v[94:95], v[216:217]
	v_pk_mul_f32 v[92:93], v[92:93], v[218:219]
	v_add_f32_dpp v60, v60, v60 quad_perm:[1,0,3,2] row_mask:0xf bank_mask:0xf bound_ctrl:1
	v_add_f32_dpp v62, v62, v62 quad_perm:[1,0,3,2] row_mask:0xf bank_mask:0xf bound_ctrl:1
	v_pk_fma_f32 v[94:95], v[236:237], v[228:229], v[94:95] op_sel_hi:[0,1,1]
	v_add_f32_dpp v60, v60, v60 quad_perm:[2,3,0,1] row_mask:0xf bank_mask:0xf bound_ctrl:1
	v_add_f32_dpp v62, v62, v62 quad_perm:[2,3,0,1] row_mask:0xf bank_mask:0xf bound_ctrl:1
	v_pk_fma_f32 v[92:93], v[236:237], v[230:231], v[92:93] op_sel_hi:[0,1,1]
	v_add_f32_dpp v60, v60, v60 row_half_mirror row_mask:0xf bank_mask:0xf bound_ctrl:1
	v_add_f32_dpp v62, v62, v62 row_half_mirror row_mask:0xf bank_mask:0xf bound_ctrl:1
	ds_read_b128 v[220:223], v74 offset:28672
	v_add_f32_dpp v60, v60, v60 row_mirror row_mask:0xf bank_mask:0xf bound_ctrl:1
	v_add_f32_dpp v62, v62, v62 row_mirror row_mask:0xf bank_mask:0xf bound_ctrl:1
	ds_read_b128 v[228:231], v74 offset:29184
	ds_read_b32 v236, v75 offset:29696
	v_pk_fma_f32 v[94:95], v[224:225], v[60:61], v[94:95] op_sel_hi:[1,0,1] neg_lo:[1,0,0] neg_hi:[1,0,0]
	v_pk_fma_f32 v[92:93], v[226:227], v[60:61], v[92:93] op_sel_hi:[1,0,1] neg_lo:[1,0,0] neg_hi:[1,0,0]
	v_pk_mul_f32 v[238:239], v[224:225], v[62:63] op_sel_hi:[1,0]
	v_pk_mul_f32 v[240:241], v[226:227], v[62:63] op_sel_hi:[1,0]
	ds_read_b128 v[224:227], v74 offset:28928
	v_pk_mul_f32 v[64:65], v[232:233], v[94:95]
	v_pk_fma_f32 v[88:89], v[88:89], v[216:217], v[238:239] neg_lo:[0,0,1] neg_hi:[0,0,1]
	v_pk_fma_f32 v[90:91], v[90:91], v[218:219], v[240:241] neg_lo:[0,0,1] neg_hi:[0,0,1]
	ds_read_b128 v[216:219], v74 offset:28416
	v_pk_fma_f32 v[64:65], v[234:235], v[92:93], v[64:65]
	v_pk_mul_f32 v[66:67], v[232:233], v[88:89]
	v_pk_fma_f32 v[66:67], v[234:235], v[90:91], v[66:67]
	ds_read_b128 v[232:235], v74 offset:29440
	v_add_f32_e32 v144, v64, v65
	v_add_f32_e32 v165, v66, v67
	s_waitcnt lgkmcnt(6)
	v_pk_mul_f32 v[60:61], v[94:95], v[126:127]
	v_pk_mul_f32 v[62:63], v[88:89], v[126:127]
	v_pk_fma_f32 v[60:61], v[92:93], v[128:129], v[60:61]
	v_pk_fma_f32 v[62:63], v[90:91], v[128:129], v[62:63]
	v_add_f32_e32 v60, v60, v61
	v_add_f32_e32 v62, v62, v63
	v_pk_mul_f32 v[94:95], v[94:95], v[122:123]
	v_pk_mul_f32 v[92:93], v[92:93], v[124:125]
	v_add_f32_dpp v60, v60, v60 quad_perm:[1,0,3,2] row_mask:0xf bank_mask:0xf bound_ctrl:1
	v_add_f32_dpp v62, v62, v62 quad_perm:[1,0,3,2] row_mask:0xf bank_mask:0xf bound_ctrl:1
	v_pk_fma_f32 v[94:95], v[142:143], v[134:135], v[94:95] op_sel_hi:[0,1,1]
	v_add_f32_dpp v60, v60, v60 quad_perm:[2,3,0,1] row_mask:0xf bank_mask:0xf bound_ctrl:1
	v_add_f32_dpp v62, v62, v62 quad_perm:[2,3,0,1] row_mask:0xf bank_mask:0xf bound_ctrl:1
	v_pk_fma_f32 v[92:93], v[142:143], v[136:137], v[92:93] op_sel_hi:[0,1,1]
	v_add_f32_dpp v60, v60, v60 row_half_mirror row_mask:0xf bank_mask:0xf bound_ctrl:1
	v_add_f32_dpp v62, v62, v62 row_half_mirror row_mask:0xf bank_mask:0xf bound_ctrl:1
	ds_read_b128 v[126:129], v74 offset:30208
	v_add_f32_dpp v60, v60, v60 row_mirror row_mask:0xf bank_mask:0xf bound_ctrl:1
	v_add_f32_dpp v62, v62, v62 row_mirror row_mask:0xf bank_mask:0xf bound_ctrl:1
	ds_read_b128 v[134:137], v74 offset:30720
	ds_read_b32 v142, v75 offset:31232
	v_pk_fma_f32 v[94:95], v[130:131], v[60:61], v[94:95] op_sel_hi:[1,0,1] neg_lo:[1,0,0] neg_hi:[1,0,0]
	v_pk_fma_f32 v[92:93], v[132:133], v[60:61], v[92:93] op_sel_hi:[1,0,1] neg_lo:[1,0,0] neg_hi:[1,0,0]
	v_pk_mul_f32 v[238:239], v[130:131], v[62:63] op_sel_hi:[1,0]
	v_pk_mul_f32 v[240:241], v[132:133], v[62:63] op_sel_hi:[1,0]
	ds_read_b128 v[130:133], v74 offset:30464
	v_pk_mul_f32 v[64:65], v[138:139], v[94:95]
	v_pk_fma_f32 v[88:89], v[88:89], v[122:123], v[238:239] neg_lo:[0,0,1] neg_hi:[0,0,1]
	v_pk_fma_f32 v[90:91], v[90:91], v[124:125], v[240:241] neg_lo:[0,0,1] neg_hi:[0,0,1]
	ds_read_b128 v[122:125], v74 offset:29952
	v_pk_fma_f32 v[64:65], v[140:141], v[92:93], v[64:65]
	v_pk_mul_f32 v[66:67], v[138:139], v[88:89]
	v_pk_fma_f32 v[66:67], v[140:141], v[90:91], v[66:67]
	ds_read_b128 v[138:141], v74 offset:30976
	v_add_f32_e32 v145, v64, v65
	v_add_f32_e32 v166, v66, v67
	s_waitcnt lgkmcnt(6)
	v_pk_mul_f32 v[60:61], v[94:95], v[220:221]
	v_pk_mul_f32 v[62:63], v[88:89], v[220:221]
	v_pk_fma_f32 v[60:61], v[92:93], v[222:223], v[60:61]
	v_pk_fma_f32 v[62:63], v[90:91], v[222:223], v[62:63]
	v_add_f32_e32 v60, v60, v61
	v_add_f32_e32 v62, v62, v63
	v_pk_mul_f32 v[94:95], v[94:95], v[216:217]
	v_pk_mul_f32 v[92:93], v[92:93], v[218:219]
	v_add_f32_dpp v60, v60, v60 quad_perm:[1,0,3,2] row_mask:0xf bank_mask:0xf bound_ctrl:1
	v_add_f32_dpp v62, v62, v62 quad_perm:[1,0,3,2] row_mask:0xf bank_mask:0xf bound_ctrl:1
	v_pk_fma_f32 v[94:95], v[236:237], v[228:229], v[94:95] op_sel_hi:[0,1,1]
	v_add_f32_dpp v60, v60, v60 quad_perm:[2,3,0,1] row_mask:0xf bank_mask:0xf bound_ctrl:1
	v_add_f32_dpp v62, v62, v62 quad_perm:[2,3,0,1] row_mask:0xf bank_mask:0xf bound_ctrl:1
	v_pk_fma_f32 v[92:93], v[236:237], v[230:231], v[92:93] op_sel_hi:[0,1,1]
	v_add_f32_dpp v60, v60, v60 row_half_mirror row_mask:0xf bank_mask:0xf bound_ctrl:1
	v_add_f32_dpp v62, v62, v62 row_half_mirror row_mask:0xf bank_mask:0xf bound_ctrl:1
	ds_read_b128 v[220:223], v74 offset:31744
	v_add_f32_dpp v60, v60, v60 row_mirror row_mask:0xf bank_mask:0xf bound_ctrl:1
	v_add_f32_dpp v62, v62, v62 row_mirror row_mask:0xf bank_mask:0xf bound_ctrl:1
	ds_read_b128 v[228:231], v74 offset:32256
	ds_read_b32 v236, v75 offset:32768
	v_pk_fma_f32 v[94:95], v[224:225], v[60:61], v[94:95] op_sel_hi:[1,0,1] neg_lo:[1,0,0] neg_hi:[1,0,0]
	v_pk_fma_f32 v[92:93], v[226:227], v[60:61], v[92:93] op_sel_hi:[1,0,1] neg_lo:[1,0,0] neg_hi:[1,0,0]
	v_pk_mul_f32 v[238:239], v[224:225], v[62:63] op_sel_hi:[1,0]
	v_pk_mul_f32 v[240:241], v[226:227], v[62:63] op_sel_hi:[1,0]
	ds_read_b128 v[224:227], v74 offset:32000
	v_pk_mul_f32 v[64:65], v[232:233], v[94:95]
	v_pk_fma_f32 v[88:89], v[88:89], v[216:217], v[238:239] neg_lo:[0,0,1] neg_hi:[0,0,1]
	v_pk_fma_f32 v[90:91], v[90:91], v[218:219], v[240:241] neg_lo:[0,0,1] neg_hi:[0,0,1]
	ds_read_b128 v[216:219], v74 offset:31488
	v_pk_fma_f32 v[64:65], v[234:235], v[92:93], v[64:65]
	v_pk_mul_f32 v[66:67], v[232:233], v[88:89]
	v_pk_fma_f32 v[66:67], v[234:235], v[90:91], v[66:67]
	ds_read_b128 v[232:235], v74 offset:32512
	v_add_f32_e32 v146, v64, v65
	v_add_f32_e32 v167, v66, v67
	s_waitcnt lgkmcnt(6)
; template <bool DUAL>
; __device__ __forceinline__ void rwkv_tile(const Params& p, int l, int tile, unsigned char* smem) {
;     ...
;       for (int i = 0; i < 32; ++i) {
;         const int inx = (i + 1) & 31;
;         const float4 nw4 = *(const float4*)(rp + inx * 384), nkk4 = *(const float4*)(rp + inx * 384 + 64), nkb4 = *(const float4*)(rp + inx * 384 + 128);
;         const float4 nkd4 = *(const float4*)(rp + inx * 384 + 192), nr4 = *(const float4*)(rp + inx * 384 + 256);
;         const float nv = vp[inx * 384];
;         v2f t = sA * (v2f){kk4.x, kk4.y};
;         t = sB * (v2f){kk4.z, kk4.w} + t;
;         float sa = t.x + t.y, ia = 0.f;
;         if (DUAL) {
;           v2f ti = iA * (v2f){kk4.x, kk4.y};
;           ti = iB * (v2f){kk4.z, kk4.w} + ti;
;           ia = ti.x + ti.y;
;           sa += dppf<0xB1>(sa); ia += dppf<0xB1>(ia);
;           sa += dppf<0x4E>(sa); ia += dppf<0x4E>(ia);
;           sa += dppf<0x141>(sa); ia += dppf<0x141>(ia);
;           sa += dppf<0x140>(sa); ia += dppf<0x140>(ia);
;         } else {
;           sa = sum16(sa);
;         }
;         v2f cA = sA * (v2f){w4.x, w4.y} + (v2f){kd4.x, kd4.y} * v;
;         v2f cB = sB * (v2f){w4.z, w4.w} + (v2f){kd4.z, kd4.w} * v;
;         sA = cA - (v2f){kb4.x, kb4.y} * sa;
;         sB = cB - (v2f){kb4.z, kb4.w} * sa;
;         v2f u = sA * (v2f){r4.x, r4.y};
;         u = sB * (v2f){r4.z, r4.w} + u;
;         float y = u.x + u.y, g = 0.f;
;         if (DUAL) {
;           iA = iA * (v2f){w4.x, w4.y} - (v2f){kb4.x, kb4.y} * ia;
;           iB = iB * (v2f){w4.z, w4.w} - (v2f){kb4.z, kb4.w} * ia;
;           v2f ui = iA * (v2f){r4.x, r4.y};
;           ui = iB * (v2f){r4.z, r4.w} + ui;
;           g = ui.x + ui.y;
;           y += dppf<0xB1>(y); g += dppf<0xB1>(g);
;           y += dppf<0x4E>(y); g += dppf<0x4E>(g);
;           y += dppf<0x141>(y); g += dppf<0x141>(g);
;           y += dppf<0x140>(y); g += dppf<0x140>(g);
;           if (fr == (i & 15)) gkeep = g;
;         } else {
;           y = sum16(y);
;         }
;         if (fr == (i & 15)) ykeep = y;
;         if ((i & 15) == 15) {
;           const int ii = (i & 16) + fr;
;           const int ri = (d == 0) ? ii + 1 : 32 - ii;
;           const int pi = plo - 1 + ri;
;           p.yR[((size_t)d * TOK + rowbase + pi) * 256 + h * 64 + row] = f2bf(ykeep);
	v_pk_mul_f32 v[60:61], v[94:95], v[126:127]
	v_pk_mul_f32 v[62:63], v[88:89], v[126:127]
	v_pk_fma_f32 v[60:61], v[92:93], v[128:129], v[60:61]
	v_pk_fma_f32 v[62:63], v[90:91], v[128:129], v[62:63]
	v_add_f32_e32 v60, v60, v61
	v_add_f32_e32 v62, v62, v63
	v_pk_mul_f32 v[94:95], v[94:95], v[122:123]
	v_pk_mul_f32 v[92:93], v[92:93], v[124:125]
	v_add_f32_dpp v60, v60, v60 quad_perm:[1,0,3,2] row_mask:0xf bank_mask:0xf bound_ctrl:1
	v_add_f32_dpp v62, v62, v62 quad_perm:[1,0,3,2] row_mask:0xf bank_mask:0xf bound_ctrl:1
	v_pk_fma_f32 v[94:95], v[142:143], v[134:135], v[94:95] op_sel_hi:[0,1,1]
	v_add_f32_dpp v60, v60, v60 quad_perm:[2,3,0,1] row_mask:0xf bank_mask:0xf bound_ctrl:1
	v_add_f32_dpp v62, v62, v62 quad_perm:[2,3,0,1] row_mask:0xf bank_mask:0xf bound_ctrl:1
	v_pk_fma_f32 v[92:93], v[142:143], v[136:137], v[92:93] op_sel_hi:[0,1,1]
	v_add_f32_dpp v60, v60, v60 row_half_mirror row_mask:0xf bank_mask:0xf bound_ctrl:1
	v_add_f32_dpp v62, v62, v62 row_half_mirror row_mask:0xf bank_mask:0xf bound_ctrl:1
	ds_read_b128 v[126:129], v74 offset:33280
	v_add_f32_dpp v60, v60, v60 row_mirror row_mask:0xf bank_mask:0xf bound_ctrl:1
	v_add_f32_dpp v62, v62, v62 row_mirror row_mask:0xf bank_mask:0xf bound_ctrl:1
	ds_read_b128 v[134:137], v74 offset:33792
	ds_read_b32 v142, v75 offset:34304
	v_pk_fma_f32 v[94:95], v[130:131], v[60:61], v[94:95] op_sel_hi:[1,0,1] neg_lo:[1,0,0] neg_hi:[1,0,0]
	v_pk_fma_f32 v[92:93], v[132:133], v[60:61], v[92:93] op_sel_hi:[1,0,1] neg_lo:[1,0,0] neg_hi:[1,0,0]
	v_pk_mul_f32 v[238:239], v[130:131], v[62:63] op_sel_hi:[1,0]
	v_pk_mul_f32 v[240:241], v[132:133], v[62:63] op_sel_hi:[1,0]
	ds_read_b128 v[130:133], v74 offset:33536
	v_pk_mul_f32 v[64:65], v[138:139], v[94:95]
	v_pk_fma_f32 v[88:89], v[88:89], v[122:123], v[238:239] neg_lo:[0,0,1] neg_hi:[0,0,1]
	v_pk_fma_f32 v[90:91], v[90:91], v[124:125], v[240:241] neg_lo:[0,0,1] neg_hi:[0,0,1]
	ds_read_b128 v[122:125], v74 offset:33024
	v_pk_fma_f32 v[64:65], v[140:141], v[92:93], v[64:65]
	v_pk_mul_f32 v[66:67], v[138:139], v[88:89]
	v_pk_fma_f32 v[66:67], v[140:141], v[90:91], v[66:67]
	ds_read_b128 v[138:141], v74 offset:34048
	v_add_f32_e32 v147, v64, v65
	v_add_f32_e32 v168, v66, v67
	s_waitcnt lgkmcnt(6)
	v_pk_mul_f32 v[60:61], v[94:95], v[220:221]
	v_pk_mul_f32 v[62:63], v[88:89], v[220:221]
	v_pk_fma_f32 v[60:61], v[92:93], v[222:223], v[60:61]
	v_pk_fma_f32 v[62:63], v[90:91], v[222:223], v[62:63]
	v_add_f32_e32 v60, v60, v61
	v_add_f32_e32 v62, v62, v63
	v_pk_mul_f32 v[94:95], v[94:95], v[216:217]
	v_pk_mul_f32 v[92:93], v[92:93], v[218:219]
	v_add_f32_dpp v60, v60, v60 quad_perm:[1,0,3,2] row_mask:0xf bank_mask:0xf bound_ctrl:1
	v_add_f32_dpp v62, v62, v62 quad_perm:[1,0,3,2] row_mask:0xf bank_mask:0xf bound_ctrl:1
	v_pk_fma_f32 v[94:95], v[236:237], v[228:229], v[94:95] op_sel_hi:[0,1,1]
	v_add_f32_dpp v60, v60, v60 quad_perm:[2,3,0,1] row_mask:0xf bank_mask:0xf bound_ctrl:1
	v_add_f32_dpp v62, v62, v62 quad_perm:[2,3,0,1] row_mask:0xf bank_mask:0xf bound_ctrl:1
	v_pk_fma_f32 v[92:93], v[236:237], v[230:231], v[92:93] op_sel_hi:[0,1,1]
	v_add_f32_dpp v60, v60, v60 row_half_mirror row_mask:0xf bank_mask:0xf bound_ctrl:1
	v_add_f32_dpp v62, v62, v62 row_half_mirror row_mask:0xf bank_mask:0xf bound_ctrl:1
	ds_read_b128 v[220:223], v74 offset:34816
	v_add_f32_dpp v60, v60, v60 row_mirror row_mask:0xf bank_mask:0xf bound_ctrl:1
	v_add_f32_dpp v62, v62, v62 row_mirror row_mask:0xf bank_mask:0xf bound_ctrl:1
	ds_read_b128 v[228:231], v74 offset:35328
	ds_read_b32 v236, v75 offset:35840
	v_pk_fma_f32 v[94:95], v[224:225], v[60:61], v[94:95] op_sel_hi:[1,0,1] neg_lo:[1,0,0] neg_hi:[1,0,0]
	v_pk_fma_f32 v[92:93], v[226:227], v[60:61], v[92:93] op_sel_hi:[1,0,1] neg_lo:[1,0,0] neg_hi:[1,0,0]
	v_pk_mul_f32 v[238:239], v[224:225], v[62:63] op_sel_hi:[1,0]
	v_pk_mul_f32 v[240:241], v[226:227], v[62:63] op_sel_hi:[1,0]
	ds_read_b128 v[224:227], v74 offset:35072
	v_pk_mul_f32 v[64:65], v[232:233], v[94:95]
	v_pk_fma_f32 v[88:89], v[88:89], v[216:217], v[238:239] neg_lo:[0,0,1] neg_hi:[0,0,1]
	v_pk_fma_f32 v[90:91], v[90:91], v[218:219], v[240:241] neg_lo:[0,0,1] neg_hi:[0,0,1]
	ds_read_b128 v[216:219], v74 offset:34560
	v_pk_fma_f32 v[64:65], v[234:235], v[92:93], v[64:65]
	v_pk_mul_f32 v[66:67], v[232:233], v[88:89]
	v_pk_fma_f32 v[66:67], v[234:235], v[90:91], v[66:67]
	ds_read_b128 v[232:235], v74 offset:35584
	v_add_f32_e32 v148, v64, v65
	v_add_f32_e32 v169, v66, v67
	s_waitcnt lgkmcnt(6)
	v_pk_mul_f32 v[60:61], v[94:95], v[126:127]
	v_pk_mul_f32 v[62:63], v[88:89], v[126:127]
	v_pk_fma_f32 v[60:61], v[92:93], v[128:129], v[60:61]
	v_pk_fma_f32 v[62:63], v[90:91], v[128:129], v[62:63]
	v_add_f32_e32 v60, v60, v61
	v_add_f32_e32 v62, v62, v63
	v_pk_mul_f32 v[94:95], v[94:95], v[122:123]
	v_pk_mul_f32 v[92:93], v[92:93], v[124:125]
	v_add_f32_dpp v60, v60, v60 quad_perm:[1,0,3,2] row_mask:0xf bank_mask:0xf bound_ctrl:1
	v_add_f32_dpp v62, v62, v62 quad_perm:[1,0,3,2] row_mask:0xf bank_mask:0xf bound_ctrl:1
	v_pk_fma_f32 v[94:95], v[142:143], v[134:135], v[94:95] op_sel_hi:[0,1,1]
	v_add_f32_dpp v60, v60, v60 quad_perm:[2,3,0,1] row_mask:0xf bank_mask:0xf bound_ctrl:1
	v_add_f32_dpp v62, v62, v62 quad_perm:[2,3,0,1] row_mask:0xf bank_mask:0xf bound_ctrl:1
	v_pk_fma_f32 v[92:93], v[142:143], v[136:137], v[92:93] op_sel_hi:[0,1,1]
	v_add_f32_dpp v60, v60, v60 row_half_mirror row_mask:0xf bank_mask:0xf bound_ctrl:1
	v_add_f32_dpp v62, v62, v62 row_half_mirror row_mask:0xf bank_mask:0xf bound_ctrl:1
	ds_read_b128 v[126:129], v74 offset:36352
	v_add_f32_dpp v60, v60, v60 row_mirror row_mask:0xf bank_mask:0xf bound_ctrl:1
	v_add_f32_dpp v62, v62, v62 row_mirror row_mask:0xf bank_mask:0xf bound_ctrl:1
	ds_read_b128 v[134:137], v74 offset:36864
	ds_read_b32 v142, v75 offset:37376
	v_pk_fma_f32 v[94:95], v[130:131], v[60:61], v[94:95] op_sel_hi:[1,0,1] neg_lo:[1,0,0] neg_hi:[1,0,0]
	v_pk_fma_f32 v[92:93], v[132:133], v[60:61], v[92:93] op_sel_hi:[1,0,1] neg_lo:[1,0,0] neg_hi:[1,0,0]
	v_pk_mul_f32 v[238:239], v[130:131], v[62:63] op_sel_hi:[1,0]
	v_pk_mul_f32 v[240:241], v[132:133], v[62:63] op_sel_hi:[1,0]
	ds_read_b128 v[130:133], v74 offset:36608
	v_pk_mul_f32 v[64:65], v[138:139], v[94:95]
	v_pk_fma_f32 v[88:89], v[88:89], v[122:123], v[238:239] neg_lo:[0,0,1] neg_hi:[0,0,1]
	v_pk_fma_f32 v[90:91], v[90:91], v[124:125], v[240:241] neg_lo:[0,0,1] neg_hi:[0,0,1]
	ds_read_b128 v[122:125], v74 offset:36096
	v_pk_fma_f32 v[64:65], v[140:141], v[92:93], v[64:65]
	v_pk_mul_f32 v[66:67], v[138:139], v[88:89]
	v_pk_fma_f32 v[66:67], v[140:141], v[90:91], v[66:67]
	ds_read_b128 v[138:141], v74 offset:37120
	v_add_f32_e32 v149, v64, v65
	v_add_f32_e32 v170, v66, v67
	s_waitcnt lgkmcnt(6)
; template <bool DUAL>
; __device__ __forceinline__ void rwkv_tile(const Params& p, int l, int tile, unsigned char* smem) {
;     ...
;       for (int i = 0; i < 32; ++i) {
;         const int inx = (i + 1) & 31;
;         const float4 nw4 = *(const float4*)(rp + inx * 384), nkk4 = *(const float4*)(rp + inx * 384 + 64), nkb4 = *(const float4*)(rp + inx * 384 + 128);
;         const float4 nkd4 = *(const float4*)(rp + inx * 384 + 192), nr4 = *(const float4*)(rp + inx * 384 + 256);
;         const float nv = vp[inx * 384];
;         v2f t = sA * (v2f){kk4.x, kk4.y};
;         t = sB * (v2f){kk4.z, kk4.w} + t;
;         float sa = t.x + t.y, ia = 0.f;
;         if (DUAL) {
;           v2f ti = iA * (v2f){kk4.x, kk4.y};
;           ti = iB * (v2f){kk4.z, kk4.w} + ti;
;           ia = ti.x + ti.y;
;           sa += dppf<0xB1>(sa); ia += dppf<0xB1>(ia);
;           sa += dppf<0x4E>(sa); ia += dppf<0x4E>(ia);
;           sa += dppf<0x141>(sa); ia += dppf<0x141>(ia);
;           sa += dppf<0x140>(sa); ia += dppf<0x140>(ia);
;         } else {
;           sa = sum16(sa);
;         }
;         v2f cA = sA * (v2f){w4.x, w4.y} + (v2f){kd4.x, kd4.y} * v;
;         v2f cB = sB * (v2f){w4.z, w4.w} + (v2f){kd4.z, kd4.w} * v;
;         sA = cA - (v2f){kb4.x, kb4.y} * sa;
;         sB = cB - (v2f){kb4.z, kb4.w} * sa;
;         v2f u = sA * (v2f){r4.x, r4.y};
;         u = sB * (v2f){r4.z, r4.w} + u;
;         float y = u.x + u.y, g = 0.f;
;         if (DUAL) {
;           iA = iA * (v2f){w4.x, w4.y} - (v2f){kb4.x, kb4.y} * ia;
;           iB = iB * (v2f){w4.z, w4.w} - (v2f){kb4.z, kb4.w} * ia;
;           v2f ui = iA * (v2f){r4.x, r4.y};
;           ui = iB * (v2f){r4.z, r4.w} + ui;
;           g = ui.x + ui.y;
;           y += dppf<0xB1>(y); g += dppf<0xB1>(g);
;           y += dppf<0x4E>(y); g += dppf<0x4E>(g);
;           y += dppf<0x141>(y); g += dppf<0x141>(g);
;           y += dppf<0x140>(y); g += dppf<0x140>(g);
;           if (fr == (i & 15)) gkeep = g;
;         } else {
;           y = sum16(y);
;         }
;         if (fr == (i & 15)) ykeep = y;
;         if ((i & 15) == 15) {
;           const int ii = (i & 16) + fr;
;           const int ri = (d == 0) ? ii + 1 : 32 - ii;
;           const int pi = plo - 1 + ri;
;           p.yR[((size_t)d * TOK + rowbase + pi) * 256 + h * 64 + row] = f2bf(ykeep);
	v_pk_mul_f32 v[60:61], v[94:95], v[220:221]
	v_pk_mul_f32 v[62:63], v[88:89], v[220:221]
	v_pk_fma_f32 v[60:61], v[92:93], v[222:223], v[60:61]
	v_pk_fma_f32 v[62:63], v[90:91], v[222:223], v[62:63]
	v_add_f32_e32 v60, v60, v61
	v_add_f32_e32 v62, v62, v63
	v_pk_mul_f32 v[94:95], v[94:95], v[216:217]
	v_pk_mul_f32 v[92:93], v[92:93], v[218:219]
	v_add_f32_dpp v60, v60, v60 quad_perm:[1,0,3,2] row_mask:0xf bank_mask:0xf bound_ctrl:1
	v_add_f32_dpp v62, v62, v62 quad_perm:[1,0,3,2] row_mask:0xf bank_mask:0xf bound_ctrl:1
	v_pk_fma_f32 v[94:95], v[236:237], v[228:229], v[94:95] op_sel_hi:[0,1,1]
	v_add_f32_dpp v60, v60, v60 quad_perm:[2,3,0,1] row_mask:0xf bank_mask:0xf bound_ctrl:1
	v_add_f32_dpp v62, v62, v62 quad_perm:[2,3,0,1] row_mask:0xf bank_mask:0xf bound_ctrl:1
	v_pk_fma_f32 v[92:93], v[236:237], v[230:231], v[92:93] op_sel_hi:[0,1,1]
	v_add_f32_dpp v60, v60, v60 row_half_mirror row_mask:0xf bank_mask:0xf bound_ctrl:1
	v_add_f32_dpp v62, v62, v62 row_half_mirror row_mask:0xf bank_mask:0xf bound_ctrl:1
	ds_read_b128 v[220:223], v74 offset:37888
	v_add_f32_dpp v60, v60, v60 row_mirror row_mask:0xf bank_mask:0xf bound_ctrl:1
	v_add_f32_dpp v62, v62, v62 row_mirror row_mask:0xf bank_mask:0xf bound_ctrl:1
	ds_read_b128 v[228:231], v74 offset:38400
	ds_read_b32 v236, v75 offset:38912
	v_pk_fma_f32 v[94:95], v[224:225], v[60:61], v[94:95] op_sel_hi:[1,0,1] neg_lo:[1,0,0] neg_hi:[1,0,0]
	v_pk_fma_f32 v[92:93], v[226:227], v[60:61], v[92:93] op_sel_hi:[1,0,1] neg_lo:[1,0,0] neg_hi:[1,0,0]
	v_pk_mul_f32 v[238:239], v[224:225], v[62:63] op_sel_hi:[1,0]
	v_pk_mul_f32 v[240:241], v[226:227], v[62:63] op_sel_hi:[1,0]
	ds_read_b128 v[224:227], v74 offset:38144
	v_pk_mul_f32 v[64:65], v[232:233], v[94:95]
	v_pk_fma_f32 v[88:89], v[88:89], v[216:217], v[238:239] neg_lo:[0,0,1] neg_hi:[0,0,1]
	v_pk_fma_f32 v[90:91], v[90:91], v[218:219], v[240:241] neg_lo:[0,0,1] neg_hi:[0,0,1]
	ds_read_b128 v[216:219], v74 offset:37632
	v_pk_fma_f32 v[64:65], v[234:235], v[92:93], v[64:65]
	v_pk_mul_f32 v[66:67], v[232:233], v[88:89]
	v_pk_fma_f32 v[66:67], v[234:235], v[90:91], v[66:67]
	ds_read_b128 v[232:235], v74 offset:38656
	v_add_f32_e32 v150, v64, v65
	v_add_f32_e32 v171, v66, v67
	s_waitcnt lgkmcnt(6)
	v_pk_mul_f32 v[60:61], v[94:95], v[126:127]
	v_pk_mul_f32 v[62:63], v[88:89], v[126:127]
	v_pk_fma_f32 v[60:61], v[92:93], v[128:129], v[60:61]
	v_pk_fma_f32 v[62:63], v[90:91], v[128:129], v[62:63]
	v_add_f32_e32 v60, v60, v61
	v_add_f32_e32 v62, v62, v63
	v_pk_mul_f32 v[94:95], v[94:95], v[122:123]
	v_pk_mul_f32 v[92:93], v[92:93], v[124:125]
	v_add_f32_dpp v60, v60, v60 quad_perm:[1,0,3,2] row_mask:0xf bank_mask:0xf bound_ctrl:1
	v_add_f32_dpp v62, v62, v62 quad_perm:[1,0,3,2] row_mask:0xf bank_mask:0xf bound_ctrl:1
	v_pk_fma_f32 v[94:95], v[142:143], v[134:135], v[94:95] op_sel_hi:[0,1,1]
	v_add_f32_dpp v60, v60, v60 quad_perm:[2,3,0,1] row_mask:0xf bank_mask:0xf bound_ctrl:1
	v_add_f32_dpp v62, v62, v62 quad_perm:[2,3,0,1] row_mask:0xf bank_mask:0xf bound_ctrl:1
	v_pk_fma_f32 v[92:93], v[142:143], v[136:137], v[92:93] op_sel_hi:[0,1,1]
	v_add_f32_dpp v60, v60, v60 row_half_mirror row_mask:0xf bank_mask:0xf bound_ctrl:1
	v_add_f32_dpp v62, v62, v62 row_half_mirror row_mask:0xf bank_mask:0xf bound_ctrl:1
	ds_read_b128 v[126:129], v74 offset:39424
	v_add_f32_dpp v60, v60, v60 row_mirror row_mask:0xf bank_mask:0xf bound_ctrl:1
	v_add_f32_dpp v62, v62, v62 row_mirror row_mask:0xf bank_mask:0xf bound_ctrl:1
	ds_read_b128 v[134:137], v74 offset:39936
	ds_read_b32 v142, v75 offset:40448
	v_pk_fma_f32 v[94:95], v[130:131], v[60:61], v[94:95] op_sel_hi:[1,0,1] neg_lo:[1,0,0] neg_hi:[1,0,0]
	v_pk_fma_f32 v[92:93], v[132:133], v[60:61], v[92:93] op_sel_hi:[1,0,1] neg_lo:[1,0,0] neg_hi:[1,0,0]
	v_pk_mul_f32 v[238:239], v[130:131], v[62:63] op_sel_hi:[1,0]
	v_pk_mul_f32 v[240:241], v[132:133], v[62:63] op_sel_hi:[1,0]
	ds_read_b128 v[130:133], v74 offset:39680
	v_pk_mul_f32 v[64:65], v[138:139], v[94:95]
	v_pk_fma_f32 v[88:89], v[88:89], v[122:123], v[238:239] neg_lo:[0,0,1] neg_hi:[0,0,1]
	v_pk_fma_f32 v[90:91], v[90:91], v[124:125], v[240:241] neg_lo:[0,0,1] neg_hi:[0,0,1]
	ds_read_b128 v[122:125], v74 offset:39168
	v_pk_fma_f32 v[64:65], v[140:141], v[92:93], v[64:65]
	v_pk_mul_f32 v[66:67], v[138:139], v[88:89]
	v_pk_fma_f32 v[66:67], v[140:141], v[90:91], v[66:67]
	ds_read_b128 v[138:141], v74 offset:40192
	v_add_f32_e32 v151, v64, v65
	v_add_f32_e32 v172, v66, v67
	s_waitcnt lgkmcnt(6)
	v_pk_mul_f32 v[60:61], v[94:95], v[220:221]
	v_pk_mul_f32 v[62:63], v[88:89], v[220:221]
	v_pk_fma_f32 v[60:61], v[92:93], v[222:223], v[60:61]
	v_pk_fma_f32 v[62:63], v[90:91], v[222:223], v[62:63]
	v_add_f32_e32 v60, v60, v61
	v_add_f32_e32 v62, v62, v63
	v_pk_mul_f32 v[94:95], v[94:95], v[216:217]
	v_pk_mul_f32 v[92:93], v[92:93], v[218:219]
	v_add_f32_dpp v60, v60, v60 quad_perm:[1,0,3,2] row_mask:0xf bank_mask:0xf bound_ctrl:1
	v_add_f32_dpp v62, v62, v62 quad_perm:[1,0,3,2] row_mask:0xf bank_mask:0xf bound_ctrl:1
	v_pk_fma_f32 v[94:95], v[236:237], v[228:229], v[94:95] op_sel_hi:[0,1,1]
	v_add_f32_dpp v60, v60, v60 quad_perm:[2,3,0,1] row_mask:0xf bank_mask:0xf bound_ctrl:1
	v_add_f32_dpp v62, v62, v62 quad_perm:[2,3,0,1] row_mask:0xf bank_mask:0xf bound_ctrl:1
	v_pk_fma_f32 v[92:93], v[236:237], v[230:231], v[92:93] op_sel_hi:[0,1,1]
	v_add_f32_dpp v60, v60, v60 row_half_mirror row_mask:0xf bank_mask:0xf bound_ctrl:1
	v_add_f32_dpp v62, v62, v62 row_half_mirror row_mask:0xf bank_mask:0xf bound_ctrl:1
	ds_read_b128 v[220:223], v74 offset:40960
	v_add_f32_dpp v60, v60, v60 row_mirror row_mask:0xf bank_mask:0xf bound_ctrl:1
	v_add_f32_dpp v62, v62, v62 row_mirror row_mask:0xf bank_mask:0xf bound_ctrl:1
	ds_read_b128 v[228:231], v74 offset:41472
	ds_read_b32 v236, v75 offset:41984
	v_pk_fma_f32 v[94:95], v[224:225], v[60:61], v[94:95] op_sel_hi:[1,0,1] neg_lo:[1,0,0] neg_hi:[1,0,0]
	v_pk_fma_f32 v[92:93], v[226:227], v[60:61], v[92:93] op_sel_hi:[1,0,1] neg_lo:[1,0,0] neg_hi:[1,0,0]
	v_pk_mul_f32 v[238:239], v[224:225], v[62:63] op_sel_hi:[1,0]
	v_pk_mul_f32 v[240:241], v[226:227], v[62:63] op_sel_hi:[1,0]
	ds_read_b128 v[224:227], v74 offset:41216
	v_pk_mul_f32 v[64:65], v[232:233], v[94:95]
	v_pk_fma_f32 v[88:89], v[88:89], v[216:217], v[238:239] neg_lo:[0,0,1] neg_hi:[0,0,1]
	v_pk_fma_f32 v[90:91], v[90:91], v[218:219], v[240:241] neg_lo:[0,0,1] neg_hi:[0,0,1]
	ds_read_b128 v[216:219], v74 offset:40704
	v_pk_fma_f32 v[64:65], v[234:235], v[92:93], v[64:65]
	v_pk_mul_f32 v[66:67], v[232:233], v[88:89]
	v_pk_fma_f32 v[66:67], v[234:235], v[90:91], v[66:67]
	ds_read_b128 v[232:235], v74 offset:41728
	v_add_f32_e32 v152, v64, v65
	v_add_f32_e32 v173, v66, v67
	s_waitcnt lgkmcnt(6)
; template <bool DUAL>
; __device__ __forceinline__ void rwkv_tile(const Params& p, int l, int tile, unsigned char* smem) {
;     ...
;       for (int i = 0; i < 32; ++i) {
;         const int inx = (i + 1) & 31;
;         const float4 nw4 = *(const float4*)(rp + inx * 384), nkk4 = *(const float4*)(rp + inx * 384 + 64), nkb4 = *(const float4*)(rp + inx * 384 + 128);
;         const float4 nkd4 = *(const float4*)(rp + inx * 384 + 192), nr4 = *(const float4*)(rp + inx * 384 + 256);
;         const float nv = vp[inx * 384];
;         v2f t = sA * (v2f){kk4.x, kk4.y};
;         t = sB * (v2f){kk4.z, kk4.w} + t;
;         float sa = t.x + t.y, ia = 0.f;
;         if (DUAL) {
;           v2f ti = iA * (v2f){kk4.x, kk4.y};
;           ti = iB * (v2f){kk4.z, kk4.w} + ti;
;           ia = ti.x + ti.y;
;           sa += dppf<0xB1>(sa); ia += dppf<0xB1>(ia);
;           sa += dppf<0x4E>(sa); ia += dppf<0x4E>(ia);
;           sa += dppf<0x141>(sa); ia += dppf<0x141>(ia);
;           sa += dppf<0x140>(sa); ia += dppf<0x140>(ia);
;         } else {
;           sa = sum16(sa);
;         }
;         v2f cA = sA * (v2f){w4.x, w4.y} + (v2f){kd4.x, kd4.y} * v;
;         v2f cB = sB * (v2f){w4.z, w4.w} + (v2f){kd4.z, kd4.w} * v;
;         sA = cA - (v2f){kb4.x, kb4.y} * sa;
;         sB = cB - (v2f){kb4.z, kb4.w} * sa;
;         v2f u = sA * (v2f){r4.x, r4.y};
;         u = sB * (v2f){r4.z, r4.w} + u;
;         float y = u.x + u.y, g = 0.f;
;         if (DUAL) {
;           iA = iA * (v2f){w4.x, w4.y} - (v2f){kb4.x, kb4.y} * ia;
;           iB = iB * (v2f){w4.z, w4.w} - (v2f){kb4.z, kb4.w} * ia;
;           v2f ui = iA * (v2f){r4.x, r4.y};
;           ui = iB * (v2f){r4.z, r4.w} + ui;
;           g = ui.x + ui.y;
;           y += dppf<0xB1>(y); g += dppf<0xB1>(g);
;           y += dppf<0x4E>(y); g += dppf<0x4E>(g);
;           y += dppf<0x141>(y); g += dppf<0x141>(g);
;           y += dppf<0x140>(y); g += dppf<0x140>(g);
;           if (fr == (i & 15)) gkeep = g;
;         } else {
;           y = sum16(y);
;         }
;         if (fr == (i & 15)) ykeep = y;
	v_pk_mul_f32 v[60:61], v[94:95], v[126:127]
	v_pk_mul_f32 v[62:63], v[88:89], v[126:127]
	v_pk_fma_f32 v[60:61], v[92:93], v[128:129], v[60:61]
	v_pk_fma_f32 v[62:63], v[90:91], v[128:129], v[62:63]
	v_add_f32_e32 v60, v60, v61
	v_add_f32_e32 v62, v62, v63
	v_pk_mul_f32 v[94:95], v[94:95], v[122:123]
	v_pk_mul_f32 v[92:93], v[92:93], v[124:125]
	v_add_f32_dpp v60, v60, v60 quad_perm:[1,0,3,2] row_mask:0xf bank_mask:0xf bound_ctrl:1
	v_add_f32_dpp v62, v62, v62 quad_perm:[1,0,3,2] row_mask:0xf bank_mask:0xf bound_ctrl:1
	v_pk_fma_f32 v[94:95], v[142:143], v[134:135], v[94:95] op_sel_hi:[0,1,1]
	v_add_f32_dpp v60, v60, v60 quad_perm:[2,3,0,1] row_mask:0xf bank_mask:0xf bound_ctrl:1
	v_add_f32_dpp v62, v62, v62 quad_perm:[2,3,0,1] row_mask:0xf bank_mask:0xf bound_ctrl:1
	v_pk_fma_f32 v[92:93], v[142:143], v[136:137], v[92:93] op_sel_hi:[0,1,1]
	v_add_f32_dpp v60, v60, v60 row_half_mirror row_mask:0xf bank_mask:0xf bound_ctrl:1
	v_add_f32_dpp v62, v62, v62 row_half_mirror row_mask:0xf bank_mask:0xf bound_ctrl:1
	ds_read_b128 v[126:129], v74 offset:42496
	v_add_f32_dpp v60, v60, v60 row_mirror row_mask:0xf bank_mask:0xf bound_ctrl:1
	v_add_f32_dpp v62, v62, v62 row_mirror row_mask:0xf bank_mask:0xf bound_ctrl:1
	ds_read_b128 v[134:137], v74 offset:43008
	ds_read_b32 v142, v75 offset:43520
	v_pk_fma_f32 v[94:95], v[130:131], v[60:61], v[94:95] op_sel_hi:[1,0,1] neg_lo:[1,0,0] neg_hi:[1,0,0]
	v_pk_fma_f32 v[92:93], v[132:133], v[60:61], v[92:93] op_sel_hi:[1,0,1] neg_lo:[1,0,0] neg_hi:[1,0,0]
	v_pk_mul_f32 v[238:239], v[130:131], v[62:63] op_sel_hi:[1,0]
	v_pk_mul_f32 v[240:241], v[132:133], v[62:63] op_sel_hi:[1,0]
	ds_read_b128 v[130:133], v74 offset:42752
	v_pk_mul_f32 v[64:65], v[138:139], v[94:95]
	v_pk_fma_f32 v[88:89], v[88:89], v[122:123], v[238:239] neg_lo:[0,0,1] neg_hi:[0,0,1]
	v_pk_fma_f32 v[90:91], v[90:91], v[124:125], v[240:241] neg_lo:[0,0,1] neg_hi:[0,0,1]
	ds_read_b128 v[122:125], v74 offset:42240
	v_pk_fma_f32 v[64:65], v[140:141], v[92:93], v[64:65]
	v_pk_mul_f32 v[66:67], v[138:139], v[88:89]
	v_pk_fma_f32 v[66:67], v[140:141], v[90:91], v[66:67]
	ds_read_b128 v[138:141], v74 offset:43264
	v_add_f32_e32 v153, v64, v65
	v_add_f32_e32 v174, v66, v67
	s_waitcnt lgkmcnt(6)
	v_pk_mul_f32 v[60:61], v[94:95], v[220:221]
	v_pk_mul_f32 v[62:63], v[88:89], v[220:221]
	v_pk_fma_f32 v[60:61], v[92:93], v[222:223], v[60:61]
	v_pk_fma_f32 v[62:63], v[90:91], v[222:223], v[62:63]
	v_add_f32_e32 v60, v60, v61
	v_add_f32_e32 v62, v62, v63
	v_pk_mul_f32 v[94:95], v[94:95], v[216:217]
	v_pk_mul_f32 v[92:93], v[92:93], v[218:219]
	v_add_f32_dpp v60, v60, v60 quad_perm:[1,0,3,2] row_mask:0xf bank_mask:0xf bound_ctrl:1
	v_add_f32_dpp v62, v62, v62 quad_perm:[1,0,3,2] row_mask:0xf bank_mask:0xf bound_ctrl:1
	v_pk_fma_f32 v[94:95], v[236:237], v[228:229], v[94:95] op_sel_hi:[0,1,1]
	v_add_f32_dpp v60, v60, v60 quad_perm:[2,3,0,1] row_mask:0xf bank_mask:0xf bound_ctrl:1
	v_add_f32_dpp v62, v62, v62 quad_perm:[2,3,0,1] row_mask:0xf bank_mask:0xf bound_ctrl:1
	v_pk_fma_f32 v[92:93], v[236:237], v[230:231], v[92:93] op_sel_hi:[0,1,1]
	v_add_f32_dpp v60, v60, v60 row_half_mirror row_mask:0xf bank_mask:0xf bound_ctrl:1
	v_add_f32_dpp v62, v62, v62 row_half_mirror row_mask:0xf bank_mask:0xf bound_ctrl:1
	ds_read_b128 v[220:223], v74 offset:44032
	v_add_f32_dpp v60, v60, v60 row_mirror row_mask:0xf bank_mask:0xf bound_ctrl:1
	v_add_f32_dpp v62, v62, v62 row_mirror row_mask:0xf bank_mask:0xf bound_ctrl:1
	ds_read_b128 v[228:231], v74 offset:44544
	ds_read_b32 v236, v75 offset:45056
	v_pk_fma_f32 v[94:95], v[224:225], v[60:61], v[94:95] op_sel_hi:[1,0,1] neg_lo:[1,0,0] neg_hi:[1,0,0]
	v_pk_fma_f32 v[92:93], v[226:227], v[60:61], v[92:93] op_sel_hi:[1,0,1] neg_lo:[1,0,0] neg_hi:[1,0,0]
	v_pk_mul_f32 v[238:239], v[224:225], v[62:63] op_sel_hi:[1,0]
	v_pk_mul_f32 v[240:241], v[226:227], v[62:63] op_sel_hi:[1,0]
	ds_read_b128 v[224:227], v74 offset:44288
	v_pk_mul_f32 v[64:65], v[232:233], v[94:95]
	v_pk_fma_f32 v[88:89], v[88:89], v[216:217], v[238:239] neg_lo:[0,0,1] neg_hi:[0,0,1]
	v_pk_fma_f32 v[90:91], v[90:91], v[218:219], v[240:241] neg_lo:[0,0,1] neg_hi:[0,0,1]
	ds_read_b128 v[216:219], v74 offset:43776
	v_pk_fma_f32 v[64:65], v[234:235], v[92:93], v[64:65]
	v_pk_mul_f32 v[66:67], v[232:233], v[88:89]
	v_pk_fma_f32 v[66:67], v[234:235], v[90:91], v[66:67]
	ds_read_b128 v[232:235], v74 offset:44800
	v_add_f32_e32 v154, v64, v65
	v_add_f32_e32 v175, v66, v67
	s_waitcnt lgkmcnt(6)
	v_pk_mul_f32 v[60:61], v[94:95], v[126:127]
	v_pk_mul_f32 v[62:63], v[88:89], v[126:127]
	v_pk_fma_f32 v[60:61], v[92:93], v[128:129], v[60:61]
	v_pk_fma_f32 v[62:63], v[90:91], v[128:129], v[62:63]
	v_add_f32_e32 v60, v60, v61
	v_add_f32_e32 v62, v62, v63
	v_pk_mul_f32 v[94:95], v[94:95], v[122:123]
	v_pk_mul_f32 v[92:93], v[92:93], v[124:125]
	v_add_f32_dpp v60, v60, v60 quad_perm:[1,0,3,2] row_mask:0xf bank_mask:0xf bound_ctrl:1
	v_add_f32_dpp v62, v62, v62 quad_perm:[1,0,3,2] row_mask:0xf bank_mask:0xf bound_ctrl:1
	v_pk_fma_f32 v[94:95], v[142:143], v[134:135], v[94:95] op_sel_hi:[0,1,1]
	v_add_f32_dpp v60, v60, v60 quad_perm:[2,3,0,1] row_mask:0xf bank_mask:0xf bound_ctrl:1
	v_add_f32_dpp v62, v62, v62 quad_perm:[2,3,0,1] row_mask:0xf bank_mask:0xf bound_ctrl:1
	v_pk_fma_f32 v[92:93], v[142:143], v[136:137], v[92:93] op_sel_hi:[0,1,1]
	v_add_f32_dpp v60, v60, v60 row_half_mirror row_mask:0xf bank_mask:0xf bound_ctrl:1
	v_add_f32_dpp v62, v62, v62 row_half_mirror row_mask:0xf bank_mask:0xf bound_ctrl:1
	ds_read_b128 v[126:129], v74 offset:45568
	v_add_f32_dpp v60, v60, v60 row_mirror row_mask:0xf bank_mask:0xf bound_ctrl:1
	v_add_f32_dpp v62, v62, v62 row_mirror row_mask:0xf bank_mask:0xf bound_ctrl:1
	ds_read_b128 v[134:137], v74 offset:46080
	ds_read_b32 v142, v75 offset:46592
	v_pk_fma_f32 v[94:95], v[130:131], v[60:61], v[94:95] op_sel_hi:[1,0,1] neg_lo:[1,0,0] neg_hi:[1,0,0]
	v_pk_fma_f32 v[92:93], v[132:133], v[60:61], v[92:93] op_sel_hi:[1,0,1] neg_lo:[1,0,0] neg_hi:[1,0,0]
	v_pk_mul_f32 v[238:239], v[130:131], v[62:63] op_sel_hi:[1,0]
	v_pk_mul_f32 v[240:241], v[132:133], v[62:63] op_sel_hi:[1,0]
	ds_read_b128 v[130:133], v74 offset:45824
	v_pk_mul_f32 v[64:65], v[138:139], v[94:95]
	v_pk_fma_f32 v[88:89], v[88:89], v[122:123], v[238:239] neg_lo:[0,0,1] neg_hi:[0,0,1]
	v_pk_fma_f32 v[90:91], v[90:91], v[124:125], v[240:241] neg_lo:[0,0,1] neg_hi:[0,0,1]
	ds_read_b128 v[122:125], v74 offset:45312
	v_pk_fma_f32 v[64:65], v[140:141], v[92:93], v[64:65]
	v_pk_mul_f32 v[66:67], v[138:139], v[88:89]
	v_pk_fma_f32 v[66:67], v[140:141], v[90:91], v[66:67]
	ds_read_b128 v[138:141], v74 offset:46336
	v_add_f32_e32 v155, v64, v65
	v_add_f32_e32 v176, v66, v67
	s_waitcnt lgkmcnt(6)
; template <bool DUAL>
; __device__ __forceinline__ void rwkv_tile(const Params& p, int l, int tile, unsigned char* smem) {
;     ...
;       for (int i = 0; i < 32; ++i) {
;         const int inx = (i + 1) & 31;
;         const float4 nw4 = *(const float4*)(rp + inx * 384), nkk4 = *(const float4*)(rp + inx * 384 + 64), nkb4 = *(const float4*)(rp + inx * 384 + 128);
;         const float4 nkd4 = *(const float4*)(rp + inx * 384 + 192), nr4 = *(const float4*)(rp + inx * 384 + 256);
;         const float nv = vp[inx * 384];
;         v2f t = sA * (v2f){kk4.x, kk4.y};
;         t = sB * (v2f){kk4.z, kk4.w} + t;
;         float sa = t.x + t.y, ia = 0.f;
;         if (DUAL) {
;           v2f ti = iA * (v2f){kk4.x, kk4.y};
;           ti = iB * (v2f){kk4.z, kk4.w} + ti;
;           ia = ti.x + ti.y;
;           sa += dppf<0xB1>(sa); ia += dppf<0xB1>(ia);
;           sa += dppf<0x4E>(sa); ia += dppf<0x4E>(ia);
;           sa += dppf<0x141>(sa); ia += dppf<0x141>(ia);
;           sa += dppf<0x140>(sa); ia += dppf<0x140>(ia);
;         } else {
;           sa = sum16(sa);
;         }
;         v2f cA = sA * (v2f){w4.x, w4.y} + (v2f){kd4.x, kd4.y} * v;
;         v2f cB = sB * (v2f){w4.z, w4.w} + (v2f){kd4.z, kd4.w} * v;
;         sA = cA - (v2f){kb4.x, kb4.y} * sa;
;         sB = cB - (v2f){kb4.z, kb4.w} * sa;
;         v2f u = sA * (v2f){r4.x, r4.y};
;         u = sB * (v2f){r4.z, r4.w} + u;
;         float y = u.x + u.y, g = 0.f;
;         if (DUAL) {
;           iA = iA * (v2f){w4.x, w4.y} - (v2f){kb4.x, kb4.y} * ia;
;           iB = iB * (v2f){w4.z, w4.w} - (v2f){kb4.z, kb4.w} * ia;
;           v2f ui = iA * (v2f){r4.x, r4.y};
;           ui = iB * (v2f){r4.z, r4.w} + ui;
;           g = ui.x + ui.y;
;           y += dppf<0xB1>(y); g += dppf<0xB1>(g);
;           y += dppf<0x4E>(y); g += dppf<0x4E>(g);
;           y += dppf<0x141>(y); g += dppf<0x141>(g);
;           y += dppf<0x140>(y); g += dppf<0x140>(g);
;           if (fr == (i & 15)) gkeep = g;
;         } else {
;           y = sum16(y);
;         }
;         if (fr == (i & 15)) ykeep = y;
	v_pk_mul_f32 v[60:61], v[94:95], v[220:221]
	v_pk_mul_f32 v[62:63], v[88:89], v[220:221]
	v_pk_fma_f32 v[60:61], v[92:93], v[222:223], v[60:61]
	v_pk_fma_f32 v[62:63], v[90:91], v[222:223], v[62:63]
	v_add_f32_e32 v60, v60, v61
	v_add_f32_e32 v62, v62, v63
	v_pk_mul_f32 v[94:95], v[94:95], v[216:217]
	v_pk_mul_f32 v[92:93], v[92:93], v[218:219]
	v_add_f32_dpp v60, v60, v60 quad_perm:[1,0,3,2] row_mask:0xf bank_mask:0xf bound_ctrl:1
	v_add_f32_dpp v62, v62, v62 quad_perm:[1,0,3,2] row_mask:0xf bank_mask:0xf bound_ctrl:1
	v_pk_fma_f32 v[94:95], v[236:237], v[228:229], v[94:95] op_sel_hi:[0,1,1]
	v_add_f32_dpp v60, v60, v60 quad_perm:[2,3,0,1] row_mask:0xf bank_mask:0xf bound_ctrl:1
	v_add_f32_dpp v62, v62, v62 quad_perm:[2,3,0,1] row_mask:0xf bank_mask:0xf bound_ctrl:1
	v_pk_fma_f32 v[92:93], v[236:237], v[230:231], v[92:93] op_sel_hi:[0,1,1]
	v_add_f32_dpp v60, v60, v60 row_half_mirror row_mask:0xf bank_mask:0xf bound_ctrl:1
	v_add_f32_dpp v62, v62, v62 row_half_mirror row_mask:0xf bank_mask:0xf bound_ctrl:1
	ds_read_b128 v[220:223], v74 offset:47104
	v_add_f32_dpp v60, v60, v60 row_mirror row_mask:0xf bank_mask:0xf bound_ctrl:1
	v_add_f32_dpp v62, v62, v62 row_mirror row_mask:0xf bank_mask:0xf bound_ctrl:1
	ds_read_b128 v[228:231], v74 offset:47616
	ds_read_b32 v236, v75 offset:48128
	v_pk_fma_f32 v[94:95], v[224:225], v[60:61], v[94:95] op_sel_hi:[1,0,1] neg_lo:[1,0,0] neg_hi:[1,0,0]
	v_pk_fma_f32 v[92:93], v[226:227], v[60:61], v[92:93] op_sel_hi:[1,0,1] neg_lo:[1,0,0] neg_hi:[1,0,0]
	v_pk_mul_f32 v[238:239], v[224:225], v[62:63] op_sel_hi:[1,0]
	v_pk_mul_f32 v[240:241], v[226:227], v[62:63] op_sel_hi:[1,0]
	ds_read_b128 v[224:227], v74 offset:47360
	v_pk_mul_f32 v[64:65], v[232:233], v[94:95]
	v_pk_fma_f32 v[88:89], v[88:89], v[216:217], v[238:239] neg_lo:[0,0,1] neg_hi:[0,0,1]
	v_pk_fma_f32 v[90:91], v[90:91], v[218:219], v[240:241] neg_lo:[0,0,1] neg_hi:[0,0,1]
	ds_read_b128 v[216:219], v74 offset:46848
	v_pk_fma_f32 v[64:65], v[234:235], v[92:93], v[64:65]
	v_pk_mul_f32 v[66:67], v[232:233], v[88:89]
	v_pk_fma_f32 v[66:67], v[234:235], v[90:91], v[66:67]
	ds_read_b128 v[232:235], v74 offset:47872
	v_add_f32_e32 v156, v64, v65
	v_add_f32_e32 v177, v66, v67
	s_waitcnt lgkmcnt(6)
	v_pk_mul_f32 v[60:61], v[94:95], v[126:127]
	v_pk_mul_f32 v[62:63], v[88:89], v[126:127]
	v_pk_fma_f32 v[60:61], v[92:93], v[128:129], v[60:61]
	v_pk_fma_f32 v[62:63], v[90:91], v[128:129], v[62:63]
	v_add_f32_e32 v60, v60, v61
	v_add_f32_e32 v62, v62, v63
	v_pk_mul_f32 v[94:95], v[94:95], v[122:123]
	v_pk_mul_f32 v[92:93], v[92:93], v[124:125]
	v_add_f32_dpp v60, v60, v60 quad_perm:[1,0,3,2] row_mask:0xf bank_mask:0xf bound_ctrl:1
	v_add_f32_dpp v62, v62, v62 quad_perm:[1,0,3,2] row_mask:0xf bank_mask:0xf bound_ctrl:1
	v_pk_fma_f32 v[94:95], v[142:143], v[134:135], v[94:95] op_sel_hi:[0,1,1]
	v_add_f32_dpp v60, v60, v60 quad_perm:[2,3,0,1] row_mask:0xf bank_mask:0xf bound_ctrl:1
	v_add_f32_dpp v62, v62, v62 quad_perm:[2,3,0,1] row_mask:0xf bank_mask:0xf bound_ctrl:1
	v_pk_fma_f32 v[92:93], v[142:143], v[136:137], v[92:93] op_sel_hi:[0,1,1]
	v_add_f32_dpp v60, v60, v60 row_half_mirror row_mask:0xf bank_mask:0xf bound_ctrl:1
	v_add_f32_dpp v62, v62, v62 row_half_mirror row_mask:0xf bank_mask:0xf bound_ctrl:1
	ds_read_b128 v[126:129], v74 offset:48640
	v_add_f32_dpp v60, v60, v60 row_mirror row_mask:0xf bank_mask:0xf bound_ctrl:1
	v_add_f32_dpp v62, v62, v62 row_mirror row_mask:0xf bank_mask:0xf bound_ctrl:1
	ds_read_b128 v[134:137], v74 offset:49152
	ds_read_b32 v142, v75 offset:49664
	v_pk_fma_f32 v[94:95], v[130:131], v[60:61], v[94:95] op_sel_hi:[1,0,1] neg_lo:[1,0,0] neg_hi:[1,0,0]
	v_pk_fma_f32 v[92:93], v[132:133], v[60:61], v[92:93] op_sel_hi:[1,0,1] neg_lo:[1,0,0] neg_hi:[1,0,0]
	v_pk_mul_f32 v[238:239], v[130:131], v[62:63] op_sel_hi:[1,0]
	v_pk_mul_f32 v[240:241], v[132:133], v[62:63] op_sel_hi:[1,0]
	ds_read_b128 v[130:133], v74 offset:48896
	v_pk_mul_f32 v[64:65], v[138:139], v[94:95]
	v_pk_fma_f32 v[88:89], v[88:89], v[122:123], v[238:239] neg_lo:[0,0,1] neg_hi:[0,0,1]
	v_pk_fma_f32 v[90:91], v[90:91], v[124:125], v[240:241] neg_lo:[0,0,1] neg_hi:[0,0,1]
	ds_read_b128 v[122:125], v74 offset:48384
	v_pk_fma_f32 v[64:65], v[140:141], v[92:93], v[64:65]
	v_pk_mul_f32 v[66:67], v[138:139], v[88:89]
	v_pk_fma_f32 v[66:67], v[140:141], v[90:91], v[66:67]
	ds_read_b128 v[138:141], v74 offset:49408
	v_add_f32_e32 v157, v64, v65
	v_add_f32_e32 v178, v66, v67
	s_waitcnt lgkmcnt(6)
	v_pk_mul_f32 v[60:61], v[94:95], v[220:221]
	v_pk_mul_f32 v[62:63], v[88:89], v[220:221]
	v_pk_fma_f32 v[60:61], v[92:93], v[222:223], v[60:61]
	v_pk_fma_f32 v[62:63], v[90:91], v[222:223], v[62:63]
	v_add_f32_e32 v60, v60, v61
	v_add_f32_e32 v62, v62, v63
	v_pk_mul_f32 v[94:95], v[94:95], v[216:217]
	v_pk_mul_f32 v[92:93], v[92:93], v[218:219]
	v_add_f32_dpp v60, v60, v60 quad_perm:[1,0,3,2] row_mask:0xf bank_mask:0xf bound_ctrl:1
	v_add_f32_dpp v62, v62, v62 quad_perm:[1,0,3,2] row_mask:0xf bank_mask:0xf bound_ctrl:1
	v_pk_fma_f32 v[94:95], v[236:237], v[228:229], v[94:95] op_sel_hi:[0,1,1]
	v_add_f32_dpp v60, v60, v60 quad_perm:[2,3,0,1] row_mask:0xf bank_mask:0xf bound_ctrl:1
	v_add_f32_dpp v62, v62, v62 quad_perm:[2,3,0,1] row_mask:0xf bank_mask:0xf bound_ctrl:1
	v_pk_fma_f32 v[92:93], v[236:237], v[230:231], v[92:93] op_sel_hi:[0,1,1]
	v_add_f32_dpp v60, v60, v60 row_half_mirror row_mask:0xf bank_mask:0xf bound_ctrl:1
	v_add_f32_dpp v62, v62, v62 row_half_mirror row_mask:0xf bank_mask:0xf bound_ctrl:1
	ds_read_b128 v[220:223], v69 offset:25600
	v_add_f32_dpp v60, v60, v60 row_mirror row_mask:0xf bank_mask:0xf bound_ctrl:1
	v_add_f32_dpp v62, v62, v62 row_mirror row_mask:0xf bank_mask:0xf bound_ctrl:1
	ds_read_b128 v[228:231], v69 offset:26112
	ds_read_b32 v236, v70 offset:26624
	v_pk_fma_f32 v[94:95], v[224:225], v[60:61], v[94:95] op_sel_hi:[1,0,1] neg_lo:[1,0,0] neg_hi:[1,0,0]
	v_pk_fma_f32 v[92:93], v[226:227], v[60:61], v[92:93] op_sel_hi:[1,0,1] neg_lo:[1,0,0] neg_hi:[1,0,0]
	v_pk_mul_f32 v[238:239], v[224:225], v[62:63] op_sel_hi:[1,0]
	v_pk_mul_f32 v[240:241], v[226:227], v[62:63] op_sel_hi:[1,0]
	ds_read_b128 v[224:227], v69 offset:25856
	v_pk_mul_f32 v[64:65], v[232:233], v[94:95]
	v_pk_fma_f32 v[88:89], v[88:89], v[216:217], v[238:239] neg_lo:[0,0,1] neg_hi:[0,0,1]
	v_pk_fma_f32 v[90:91], v[90:91], v[218:219], v[240:241] neg_lo:[0,0,1] neg_hi:[0,0,1]
	ds_read_b128 v[216:219], v69 offset:25344
	v_pk_fma_f32 v[64:65], v[234:235], v[92:93], v[64:65]
	v_pk_mul_f32 v[66:67], v[232:233], v[88:89]
	v_pk_fma_f32 v[66:67], v[234:235], v[90:91], v[66:67]
	ds_read_b128 v[232:235], v69 offset:26368
	v_add_f32_e32 v158, v64, v65
	v_add_f32_e32 v179, v66, v67
	s_waitcnt lgkmcnt(6)
; template <bool DUAL>
; __device__ __forceinline__ void rwkv_tile(const Params& p, int l, int tile, unsigned char* smem) {
;     ...
;         v2f t = sA * (v2f){kk4.x, kk4.y};
;         t = sB * (v2f){kk4.z, kk4.w} + t;
;         float sa = t.x + t.y, ia = 0.f;
;         if (DUAL) {
;           v2f ti = iA * (v2f){kk4.x, kk4.y};
;           ti = iB * (v2f){kk4.z, kk4.w} + ti;
;           ia = ti.x + ti.y;
;           sa += dppf<0xB1>(sa); ia += dppf<0xB1>(ia);
;           sa += dppf<0x4E>(sa); ia += dppf<0x4E>(ia);
;           sa += dppf<0x141>(sa); ia += dppf<0x141>(ia);
;           sa += dppf<0x140>(sa); ia += dppf<0x140>(ia);
;         } else {
;           sa = sum16(sa);
;         }
;         v2f cA = sA * (v2f){w4.x, w4.y} + (v2f){kd4.x, kd4.y} * v;
;         v2f cB = sB * (v2f){w4.z, w4.w} + (v2f){kd4.z, kd4.w} * v;
;         sA = cA - (v2f){kb4.x, kb4.y} * sa;
;         sB = cB - (v2f){kb4.z, kb4.w} * sa;
;         v2f u = sA * (v2f){r4.x, r4.y};
;         u = sB * (v2f){r4.z, r4.w} + u;
;         float y = u.x + u.y, g = 0.f;
;         if (DUAL) {
;           iA = iA * (v2f){w4.x, w4.y} - (v2f){kb4.x, kb4.y} * ia;
;           iB = iB * (v2f){w4.z, w4.w} - (v2f){kb4.z, kb4.w} * ia;
;           v2f ui = iA * (v2f){r4.x, r4.y};
;           ui = iB * (v2f){r4.z, r4.w} + ui;
;           g = ui.x + ui.y;
;           y += dppf<0xB1>(y); g += dppf<0xB1>(g);
;           y += dppf<0x4E>(y); g += dppf<0x4E>(g);
;           y += dppf<0x141>(y); g += dppf<0x141>(g);
;           y += dppf<0x140>(y); g += dppf<0x140>(g);
;           if (fr == (i & 15)) gkeep = g;
;         } else {
;           y = sum16(y);
;         }
;         if (fr == (i & 15)) ykeep = y;
	v_pk_mul_f32 v[60:61], v[94:95], v[126:127]
	v_pk_mul_f32 v[62:63], v[88:89], v[126:127]
	v_pk_fma_f32 v[60:61], v[92:93], v[128:129], v[60:61]
	v_pk_fma_f32 v[62:63], v[90:91], v[128:129], v[62:63]
	v_add_f32_e32 v60, v60, v61
	v_add_f32_e32 v62, v62, v63
	v_pk_mul_f32 v[94:95], v[94:95], v[122:123]
	v_pk_mul_f32 v[92:93], v[92:93], v[124:125]
	v_add_f32_dpp v60, v60, v60 quad_perm:[1,0,3,2] row_mask:0xf bank_mask:0xf bound_ctrl:1
	v_add_f32_dpp v62, v62, v62 quad_perm:[1,0,3,2] row_mask:0xf bank_mask:0xf bound_ctrl:1
	v_pk_fma_f32 v[94:95], v[142:143], v[134:135], v[94:95] op_sel_hi:[0,1,1]
	v_add_f32_dpp v60, v60, v60 quad_perm:[2,3,0,1] row_mask:0xf bank_mask:0xf bound_ctrl:1
	v_add_f32_dpp v62, v62, v62 quad_perm:[2,3,0,1] row_mask:0xf bank_mask:0xf bound_ctrl:1
	v_pk_fma_f32 v[92:93], v[142:143], v[136:137], v[92:93] op_sel_hi:[0,1,1]
	v_add_f32_dpp v60, v60, v60 row_half_mirror row_mask:0xf bank_mask:0xf bound_ctrl:1
	v_add_f32_dpp v62, v62, v62 row_half_mirror row_mask:0xf bank_mask:0xf bound_ctrl:1
	ds_read_b128 v[126:129], v69 offset:27136
	v_add_f32_dpp v60, v60, v60 row_mirror row_mask:0xf bank_mask:0xf bound_ctrl:1
	v_add_f32_dpp v62, v62, v62 row_mirror row_mask:0xf bank_mask:0xf bound_ctrl:1
	ds_read_b128 v[134:137], v69 offset:27648
	ds_read_b32 v142, v70 offset:28160
	v_pk_fma_f32 v[94:95], v[130:131], v[60:61], v[94:95] op_sel_hi:[1,0,1] neg_lo:[1,0,0] neg_hi:[1,0,0]
	v_pk_fma_f32 v[92:93], v[132:133], v[60:61], v[92:93] op_sel_hi:[1,0,1] neg_lo:[1,0,0] neg_hi:[1,0,0]
	v_pk_mul_f32 v[238:239], v[130:131], v[62:63] op_sel_hi:[1,0]
	v_pk_mul_f32 v[240:241], v[132:133], v[62:63] op_sel_hi:[1,0]
	ds_read_b128 v[130:133], v69 offset:27392
	v_pk_mul_f32 v[64:65], v[138:139], v[94:95]
	v_pk_fma_f32 v[88:89], v[88:89], v[122:123], v[238:239] neg_lo:[0,0,1] neg_hi:[0,0,1]
	v_pk_fma_f32 v[90:91], v[90:91], v[124:125], v[240:241] neg_lo:[0,0,1] neg_hi:[0,0,1]
	ds_read_b128 v[122:125], v69 offset:26880
	v_pk_fma_f32 v[64:65], v[140:141], v[92:93], v[64:65]
	v_pk_mul_f32 v[66:67], v[138:139], v[88:89]
	v_pk_fma_f32 v[66:67], v[140:141], v[90:91], v[66:67]
	ds_read_b128 v[138:141], v69 offset:27904
	v_add_f32_e32 v159, v64, v65
	v_add_f32_e32 v180, v66, v67
	v_add_f32_dpp v144, v144, v144 row_shl:8 row_mask:0xf bank_mask:0x3
	v_add_f32_dpp v144, v152, v152 row_shr:8 row_mask:0xf bank_mask:0xc
	v_add_f32_dpp v145, v145, v145 row_shl:8 row_mask:0xf bank_mask:0x3
	v_add_f32_dpp v145, v153, v153 row_shr:8 row_mask:0xf bank_mask:0xc
	v_add_f32_dpp v146, v146, v146 row_shl:8 row_mask:0xf bank_mask:0x3
	v_add_f32_dpp v146, v154, v154 row_shr:8 row_mask:0xf bank_mask:0xc
	v_add_f32_dpp v147, v147, v147 row_shl:8 row_mask:0xf bank_mask:0x3
	v_add_f32_dpp v147, v155, v155 row_shr:8 row_mask:0xf bank_mask:0xc
	v_add_f32_dpp v148, v148, v148 row_shl:8 row_mask:0xf bank_mask:0x3
	v_add_f32_dpp v148, v156, v156 row_shr:8 row_mask:0xf bank_mask:0xc
	v_add_f32_dpp v149, v149, v149 row_shl:8 row_mask:0xf bank_mask:0x3
	v_add_f32_dpp v149, v157, v157 row_shr:8 row_mask:0xf bank_mask:0xc
	v_add_f32_dpp v150, v150, v150 row_shl:8 row_mask:0xf bank_mask:0x3
	v_add_f32_dpp v150, v158, v158 row_shr:8 row_mask:0xf bank_mask:0xc
	v_add_f32_dpp v151, v151, v151 row_shl:8 row_mask:0xf bank_mask:0x3
	v_add_f32_dpp v151, v159, v159 row_shr:8 row_mask:0xf bank_mask:0xc
	v_add_f32_dpp v144, v144, v144 row_shl:4 row_mask:0xf bank_mask:0x5
	v_add_f32_dpp v144, v148, v148 row_shr:4 row_mask:0xf bank_mask:0xa
	v_add_f32_dpp v145, v145, v145 row_shl:4 row_mask:0xf bank_mask:0x5
	v_add_f32_dpp v145, v149, v149 row_shr:4 row_mask:0xf bank_mask:0xa
	v_add_f32_dpp v146, v146, v146 row_shl:4 row_mask:0xf bank_mask:0x5
	v_add_f32_dpp v146, v150, v150 row_shr:4 row_mask:0xf bank_mask:0xa
	v_add_f32_dpp v147, v147, v147 row_shl:4 row_mask:0xf bank_mask:0x5
	v_add_f32_dpp v147, v151, v151 row_shr:4 row_mask:0xf bank_mask:0xa
	v_cndmask_b32_e32 v160, v144, v146, vcc
	v_cndmask_b32_e32 v161, v146, v144, vcc
	v_cndmask_b32_e32 v163, v147, v145, vcc
	v_cndmask_b32_e32 v162, v145, v147, vcc
	v_add_f32_dpp v160, v161, v160 quad_perm:[2,3,0,1] row_mask:0xf bank_mask:0xf
	v_add_f32_dpp v162, v163, v162 quad_perm:[2,3,0,1] row_mask:0xf bank_mask:0xf
	v_cndmask_b32_e64 v181, v160, v162, s[58:59]
	v_cndmask_b32_e64 v182, v162, v160, s[58:59]
	v_add_u32_e32 v74, 0x6000, v74
	v_add_u32_e32 v75, 0x6000, v75
	v_add_f32_dpp v72, v182, v181 quad_perm:[1,0,3,2] row_mask:0xf bank_mask:0xf
	v_add_f32_dpp v165, v165, v165 row_shl:8 row_mask:0xf bank_mask:0x3
	v_add_f32_dpp v165, v173, v173 row_shr:8 row_mask:0xf bank_mask:0xc
	v_add_f32_dpp v166, v166, v166 row_shl:8 row_mask:0xf bank_mask:0x3
	v_add_f32_dpp v166, v174, v174 row_shr:8 row_mask:0xf bank_mask:0xc
	v_add_f32_dpp v167, v167, v167 row_shl:8 row_mask:0xf bank_mask:0x3
	v_add_f32_dpp v167, v175, v175 row_shr:8 row_mask:0xf bank_mask:0xc
	v_add_f32_dpp v168, v168, v168 row_shl:8 row_mask:0xf bank_mask:0x3
	v_add_f32_dpp v168, v176, v176 row_shr:8 row_mask:0xf bank_mask:0xc
	v_add_f32_dpp v169, v169, v169 row_shl:8 row_mask:0xf bank_mask:0x3
	v_add_f32_dpp v169, v177, v177 row_shr:8 row_mask:0xf bank_mask:0xc
	v_add_f32_dpp v170, v170, v170 row_shl:8 row_mask:0xf bank_mask:0x3
	v_add_f32_dpp v170, v178, v178 row_shr:8 row_mask:0xf bank_mask:0xc
	v_add_f32_dpp v171, v171, v171 row_shl:8 row_mask:0xf bank_mask:0x3
	v_add_f32_dpp v171, v179, v179 row_shr:8 row_mask:0xf bank_mask:0xc
	v_add_f32_dpp v172, v172, v172 row_shl:8 row_mask:0xf bank_mask:0x3
	v_add_f32_dpp v172, v180, v180 row_shr:8 row_mask:0xf bank_mask:0xc
	v_add_f32_dpp v165, v165, v165 row_shl:4 row_mask:0xf bank_mask:0x5
	v_add_f32_dpp v165, v169, v169 row_shr:4 row_mask:0xf bank_mask:0xa
; __device__ __forceinline__ bf16_t f2bf(float f) { return (bf16_t)(pack2(f, 0.f) & 0xffffu); }
; template <bool DUAL>
; __device__ __forceinline__ void rwkv_tile(const Params& p, int l, int tile, unsigned char* smem) {
;     ...
;         if ((i & 15) == 15) {
;           const int ii = (i & 16) + fr;
;           const int ri = (d == 0) ? ii + 1 : 32 - ii;
;           const int pi = plo - 1 + ri;
;           p.yR[((size_t)d * TOK + rowbase + pi) * 256 + h * 64 + row] = f2bf(ykeep);
;           if (DUAL) p.GID[((size_t)(d * 4 + b) * NSEG1 + (cix - CSPLIT) * 32 + ii) * 256 + h * 64 + row] = f2bf(gkeep);
	v_add_f32_dpp v166, v166, v166 row_shl:4 row_mask:0xf bank_mask:0x5
	v_add_f32_dpp v166, v170, v170 row_shr:4 row_mask:0xf bank_mask:0xa
	v_add_f32_dpp v167, v167, v167 row_shl:4 row_mask:0xf bank_mask:0x5
	v_add_f32_dpp v167, v171, v171 row_shr:4 row_mask:0xf bank_mask:0xa
	v_add_f32_dpp v168, v168, v168 row_shl:4 row_mask:0xf bank_mask:0x5
	v_add_f32_dpp v168, v172, v172 row_shr:4 row_mask:0xf bank_mask:0xa
	v_cndmask_b32_e32 v160, v165, v167, vcc
	v_cndmask_b32_e32 v161, v167, v165, vcc
	v_cndmask_b32_e32 v163, v168, v166, vcc
	v_cndmask_b32_e32 v162, v166, v168, vcc
	v_add_f32_dpp v160, v161, v160 quad_perm:[2,3,0,1] row_mask:0xf bank_mask:0xf
	v_add_f32_dpp v162, v163, v162 quad_perm:[2,3,0,1] row_mask:0xf bank_mask:0xf
	v_cndmask_b32_e64 v181, v160, v162, s[58:59]
	v_cndmask_b32_e64 v182, v162, v160, s[58:59]
	v_mov_b32_e32 v69, v102
	v_mov_b32_e32 v70, v103
	v_add_f32_dpp v73, v182, v181 quad_perm:[1,0,3,2] row_mask:0xf bank_mask:0xf
	v_mov_b32_e32 v79, v68
	v_add_u32_e32 v77, 1, v79
	v_sub_u32_e32 v76, 32, v79
	v_cndmask_b32_e64 v76, v76, v77, s[36:37]
	v_add_u32_e32 v76, s28, v76
	v_ashrrev_i32_e32 v77, 31, v76
	v_lshl_add_u64 v[76:77], s[20:21], 0, v[76:77]
	v_lshlrev_b64 v[76:77], 9, v[76:77]
	v_cvt_pk_bf16_f32 v78, v72, v72
	v_lshl_add_u64 v[76:77], v[84:85], 0, v[76:77]
	global_store_short v[76:77], v78, off
	v_or_b32_e32 v76, s53, v79
	v_mov_b32_e32 v77, s54
	v_cvt_pk_bf16_f32 v79, v73, v73
	v_lshlrev_b64 v[76:77], 9, v[76:77]
	v_lshl_add_u64 v[76:77], v[86:87], 0, v[76:77]
	global_store_short v[76:77], v79, off
	v_add_u32_e32 v68, 16, v68
	s_add_i32 s55, s55, 1
	s_cmp_lg_u32 s55, 1
	s_cbranch_scc1 .Lrw_du_fin
	s_and_b64 s[50:51], s[42:43], s[48:49]
	s_and_saveexec_b64 s[68:69], s[50:51]
	s_cbranch_execz .Lrw_du_middone
	s_waitcnt vmcnt(2)
	ds_write_b128 v104, v[32:35]
	ds_write_b128 v105, v[28:31]
	ds_write_b128 v106, v[36:39]
	s_and_saveexec_b64 s[50:51], s[44:45]
	ds_write_b128 v120, v[40:43]
	s_or_b64 exec, exec, s[50:51]
	ds_write_b128 v104, v[44:47] offset:13056
	ds_write_b128 v105, v[48:51] offset:13056
	ds_write_b128 v106, v[52:55] offset:13056
	s_mov_b64 s[50:51], exec
	s_and_b64 exec, exec, s[46:47]
	ds_write_b128 v120, v[56:59] offset:13056
	s_mov_b64 exec, s[50:51]
	s_add_i32 s1, s52, 1
	s_cmpk_ge_u32 s1, 0x87
	s_cbranch_scc1 .Lrw_du_middone
	s_lshl_b32 s64, s1, 5
	s_sub_i32 s66, 0x11e0, s64
	s_and_b64 s[0:1], s[36:37], exec
	s_cselect_b32 s64, s64, s66
	s_add_i32 s66, s64, -1
	v_add_u32_e32 v32, s66, v97
	v_lshlrev_b32_e32 v32, 11, v32
	v_mov_b32_e32 v33, v164
	v_lshl_add_u64 v[32:33], v[80:81], 0, v[32:33]
	global_load_dwordx4 v[32:35], v[32:33], off
	v_add_u32_e32 v28, s66, v98
	v_lshlrev_b32_e32 v28, 11, v28
	v_mov_b32_e32 v29, v164
	v_lshl_add_u64 v[28:29], v[80:81], 0, v[28:29]
	global_load_dwordx4 v[28:31], v[28:29], off
	v_add_u32_e32 v36, s66, v99
	v_lshlrev_b32_e32 v36, 11, v36
	v_mov_b32_e32 v37, v164
	v_lshl_add_u64 v[36:37], v[80:81], 0, v[36:37]
	global_load_dwordx4 v[36:39], v[36:37], off
	v_add_u32_e32 v44, s64, v97
	v_mov_b32_e32 v45, v164
	v_lshlrev_b64 v[44:45], 10, v[44:45]
	v_lshl_add_u64 v[44:45], v[82:83], 0, v[44:45]
	global_load_dwordx4 v[44:47], v[44:45], off
	v_add_u32_e32 v48, s64, v98
	v_mov_b32_e32 v49, v164
	v_lshlrev_b64 v[48:49], 10, v[48:49]
	v_lshl_add_u64 v[48:49], v[82:83], 0, v[48:49]
	global_load_dwordx4 v[48:51], v[48:49], off
	v_add_u32_e32 v52, s64, v99
	v_mov_b32_e32 v53, v164
	v_lshlrev_b64 v[52:53], 10, v[52:53]
	v_lshl_add_u64 v[52:53], v[82:83], 0, v[52:53]
	global_load_dwordx4 v[52:55], v[52:53], off
	s_or_b64 exec, exec, s[68:69]
	s_mov_b64 s[50:51], exec
	s_and_b64 exec, exec, s[44:45]
	v_add_u32_e32 v40, s66, v100
	v_lshlrev_b32_e32 v40, 11, v40
	v_mov_b32_e32 v41, v164
	v_lshl_add_u64 v[40:41], v[80:81], 0, v[40:41]
	global_load_dwordx4 v[40:43], v[40:41], off
	s_mov_b64 exec, s[50:51]
	s_and_b64 exec, exec, s[46:47]
	v_add_u32_e32 v56, s64, v100
	v_mov_b32_e32 v57, v164
	v_lshlrev_b64 v[56:57], 10, v[56:57]
	v_lshl_add_u64 v[56:57], v[82:83], 0, v[56:57]
	global_load_dwordx4 v[56:59], v[56:57], off
	s_mov_b64 exec, s[50:51]
	s_branch .Lrw_du_loop
.Lrw_du_middone:
	s_or_b64 exec, exec, s[68:69]
	s_branch .Lrw_du_loop
.Lrw_du_fin:
	s_branch .LBB0_1410
.Lrw_nd_scan:
	v_mov_b32_e32 v72, v99
	v_mov_b32_e32 v73, v100
	v_add_u32_e32 v68, 0x6000, v99
	v_add_u32_e32 v69, 0x6000, v100
	v_mov_b32_e32 v71, v98
	s_mov_b32 vcc_lo, 0xcccccccc
	s_mov_b32 vcc_hi, 0xcccccccc
	s_mov_b32 s58, 0xaaaaaaaa
	s_mov_b32 s59, 0xaaaaaaaa
	ds_read_b128 v[220:223], v72 offset:25600
	ds_read_b128 v[216:219], v72 offset:25344
	ds_read_b128 v[228:231], v72 offset:26112
	ds_read_b32 v236, v73 offset:26624
	ds_read_b128 v[224:227], v72 offset:25856
	ds_read_b128 v[232:235], v72 offset:26368
	ds_read_b128 v[122:125], v72 offset:27136
	ds_read_b128 v[118:121], v72 offset:26880
	ds_read_b128 v[130:133], v72 offset:27648
	ds_read_b32 v138, v73 offset:28160
	ds_read_b128 v[126:129], v72 offset:27392
	ds_read_b128 v[134:137], v72 offset:27904
	s_mov_b32 s50, 0
; template <bool DUAL>
; __device__ __forceinline__ void rwkv_tile(const Params& p, int l, int tile, unsigned char* smem) {
;     ...
;       for (int i = 0; i < 32; ++i) {
;         const int inx = (i + 1) & 31;
;         const float4 nw4 = *(const float4*)(rp + inx * 384), nkk4 = *(const float4*)(rp + inx * 384 + 64), nkb4 = *(const float4*)(rp + inx * 384 + 128);
;         const float4 nkd4 = *(const float4*)(rp + inx * 384 + 192), nr4 = *(const float4*)(rp + inx * 384 + 256);
;         const float nv = vp[inx * 384];
;         v2f t = sA * (v2f){kk4.x, kk4.y};
;         t = sB * (v2f){kk4.z, kk4.w} + t;
;         float sa = t.x + t.y, ia = 0.f;
;         if (DUAL) {
;           v2f ti = iA * (v2f){kk4.x, kk4.y};
;           ti = iB * (v2f){kk4.z, kk4.w} + ti;
;           ia = ti.x + ti.y;
;           sa += dppf<0xB1>(sa); ia += dppf<0xB1>(ia);
;           sa += dppf<0x4E>(sa); ia += dppf<0x4E>(ia);
;           sa += dppf<0x141>(sa); ia += dppf<0x141>(ia);
;           sa += dppf<0x140>(sa); ia += dppf<0x140>(ia);
;         } else {
;           sa = sum16(sa);
;         }
;         v2f cA = sA * (v2f){w4.x, w4.y} + (v2f){kd4.x, kd4.y} * v;
;         v2f cB = sB * (v2f){w4.z, w4.w} + (v2f){kd4.z, kd4.w} * v;
;         sA = cA - (v2f){kb4.x, kb4.y} * sa;
;         sB = cB - (v2f){kb4.z, kb4.w} * sa;
;         v2f u = sA * (v2f){r4.x, r4.y};
;         u = sB * (v2f){r4.z, r4.w} + u;
;         float y = u.x + u.y, g = 0.f;
.Lrw_nd_loop:
	s_waitcnt lgkmcnt(6)
	v_pk_mul_f32 v[64:65], v[60:61], v[220:221]
	v_pk_fma_f32 v[64:65], v[62:63], v[222:223], v[64:65]
	v_add_f32_e32 v64, v64, v65
	v_pk_mul_f32 v[60:61], v[60:61], v[216:217]
	v_pk_mul_f32 v[62:63], v[62:63], v[218:219]
	v_add_f32_dpp v64, v64, v64 quad_perm:[1,0,3,2] row_mask:0xf bank_mask:0xf bound_ctrl:1
	v_pk_fma_f32 v[60:61], v[236:237], v[228:229], v[60:61] op_sel_hi:[0,1,1]
	v_pk_fma_f32 v[62:63], v[236:237], v[230:231], v[62:63] op_sel_hi:[0,1,1]
	v_add_f32_dpp v64, v64, v64 quad_perm:[2,3,0,1] row_mask:0xf bank_mask:0xf bound_ctrl:1
	ds_read_b128 v[220:223], v72 offset:28672
	ds_read_b128 v[216:219], v72 offset:28416
	v_add_f32_dpp v64, v64, v64 row_half_mirror row_mask:0xf bank_mask:0xf bound_ctrl:1
	ds_read_b128 v[228:231], v72 offset:29184
	ds_read_b32 v236, v73 offset:29696
	v_add_f32_dpp v64, v64, v64 row_mirror row_mask:0xf bank_mask:0xf bound_ctrl:1
	v_pk_fma_f32 v[60:61], v[224:225], v[64:65], v[60:61] op_sel_hi:[1,0,1] neg_lo:[1,0,0] neg_hi:[1,0,0]
	v_pk_fma_f32 v[62:63], v[226:227], v[64:65], v[62:63] op_sel_hi:[1,0,1] neg_lo:[1,0,0] neg_hi:[1,0,0]
	ds_read_b128 v[224:227], v72 offset:28928
	v_pk_mul_f32 v[66:67], v[232:233], v[60:61]
	v_pk_fma_f32 v[66:67], v[234:235], v[62:63], v[66:67]
	ds_read_b128 v[232:235], v72 offset:29440
	v_add_f32_e32 v140, v66, v67
	s_waitcnt lgkmcnt(6)
	v_pk_mul_f32 v[64:65], v[60:61], v[122:123]
	v_pk_fma_f32 v[64:65], v[62:63], v[124:125], v[64:65]
	v_add_f32_e32 v64, v64, v65
	v_pk_mul_f32 v[60:61], v[60:61], v[118:119]
	v_pk_mul_f32 v[62:63], v[62:63], v[120:121]
	v_add_f32_dpp v64, v64, v64 quad_perm:[1,0,3,2] row_mask:0xf bank_mask:0xf bound_ctrl:1
	v_pk_fma_f32 v[60:61], v[138:139], v[130:131], v[60:61] op_sel_hi:[0,1,1]
	v_pk_fma_f32 v[62:63], v[138:139], v[132:133], v[62:63] op_sel_hi:[0,1,1]
	v_add_f32_dpp v64, v64, v64 quad_perm:[2,3,0,1] row_mask:0xf bank_mask:0xf bound_ctrl:1
	ds_read_b128 v[122:125], v72 offset:30208
	ds_read_b128 v[118:121], v72 offset:29952
	v_add_f32_dpp v64, v64, v64 row_half_mirror row_mask:0xf bank_mask:0xf bound_ctrl:1
	ds_read_b128 v[130:133], v72 offset:30720
	ds_read_b32 v138, v73 offset:31232
	v_add_f32_dpp v64, v64, v64 row_mirror row_mask:0xf bank_mask:0xf bound_ctrl:1
	v_pk_fma_f32 v[60:61], v[126:127], v[64:65], v[60:61] op_sel_hi:[1,0,1] neg_lo:[1,0,0] neg_hi:[1,0,0]
	v_pk_fma_f32 v[62:63], v[128:129], v[64:65], v[62:63] op_sel_hi:[1,0,1] neg_lo:[1,0,0] neg_hi:[1,0,0]
	ds_read_b128 v[126:129], v72 offset:30464
	v_pk_mul_f32 v[66:67], v[134:135], v[60:61]
	v_pk_fma_f32 v[66:67], v[136:137], v[62:63], v[66:67]
	ds_read_b128 v[134:137], v72 offset:30976
	v_add_f32_e32 v141, v66, v67
	s_waitcnt lgkmcnt(6)
	v_pk_mul_f32 v[64:65], v[60:61], v[220:221]
	v_pk_fma_f32 v[64:65], v[62:63], v[222:223], v[64:65]
	v_add_f32_e32 v64, v64, v65
	v_pk_mul_f32 v[60:61], v[60:61], v[216:217]
	v_pk_mul_f32 v[62:63], v[62:63], v[218:219]
	v_add_f32_dpp v64, v64, v64 quad_perm:[1,0,3,2] row_mask:0xf bank_mask:0xf bound_ctrl:1
	v_pk_fma_f32 v[60:61], v[236:237], v[228:229], v[60:61] op_sel_hi:[0,1,1]
	v_pk_fma_f32 v[62:63], v[236:237], v[230:231], v[62:63] op_sel_hi:[0,1,1]
	v_add_f32_dpp v64, v64, v64 quad_perm:[2,3,0,1] row_mask:0xf bank_mask:0xf bound_ctrl:1
	ds_read_b128 v[220:223], v72 offset:31744
	ds_read_b128 v[216:219], v72 offset:31488
	v_add_f32_dpp v64, v64, v64 row_half_mirror row_mask:0xf bank_mask:0xf bound_ctrl:1
	ds_read_b128 v[228:231], v72 offset:32256
	ds_read_b32 v236, v73 offset:32768
	v_add_f32_dpp v64, v64, v64 row_mirror row_mask:0xf bank_mask:0xf bound_ctrl:1
	v_pk_fma_f32 v[60:61], v[224:225], v[64:65], v[60:61] op_sel_hi:[1,0,1] neg_lo:[1,0,0] neg_hi:[1,0,0]
	v_pk_fma_f32 v[62:63], v[226:227], v[64:65], v[62:63] op_sel_hi:[1,0,1] neg_lo:[1,0,0] neg_hi:[1,0,0]
	ds_read_b128 v[224:227], v72 offset:32000
	v_pk_mul_f32 v[66:67], v[232:233], v[60:61]
	v_pk_fma_f32 v[66:67], v[234:235], v[62:63], v[66:67]
	ds_read_b128 v[232:235], v72 offset:32512
	v_add_f32_e32 v142, v66, v67
	s_waitcnt lgkmcnt(6)
	v_pk_mul_f32 v[64:65], v[60:61], v[122:123]
	v_pk_fma_f32 v[64:65], v[62:63], v[124:125], v[64:65]
	v_add_f32_e32 v64, v64, v65
	v_pk_mul_f32 v[60:61], v[60:61], v[118:119]
	v_pk_mul_f32 v[62:63], v[62:63], v[120:121]
	v_add_f32_dpp v64, v64, v64 quad_perm:[1,0,3,2] row_mask:0xf bank_mask:0xf bound_ctrl:1
	v_pk_fma_f32 v[60:61], v[138:139], v[130:131], v[60:61] op_sel_hi:[0,1,1]
	v_pk_fma_f32 v[62:63], v[138:139], v[132:133], v[62:63] op_sel_hi:[0,1,1]
	v_add_f32_dpp v64, v64, v64 quad_perm:[2,3,0,1] row_mask:0xf bank_mask:0xf bound_ctrl:1
	ds_read_b128 v[122:125], v72 offset:33280
	ds_read_b128 v[118:121], v72 offset:33024
	v_add_f32_dpp v64, v64, v64 row_half_mirror row_mask:0xf bank_mask:0xf bound_ctrl:1
	ds_read_b128 v[130:133], v72 offset:33792
	ds_read_b32 v138, v73 offset:34304
	v_add_f32_dpp v64, v64, v64 row_mirror row_mask:0xf bank_mask:0xf bound_ctrl:1
	v_pk_fma_f32 v[60:61], v[126:127], v[64:65], v[60:61] op_sel_hi:[1,0,1] neg_lo:[1,0,0] neg_hi:[1,0,0]
	v_pk_fma_f32 v[62:63], v[128:129], v[64:65], v[62:63] op_sel_hi:[1,0,1] neg_lo:[1,0,0] neg_hi:[1,0,0]
	ds_read_b128 v[126:129], v72 offset:33536
	v_pk_mul_f32 v[66:67], v[134:135], v[60:61]
	v_pk_fma_f32 v[66:67], v[136:137], v[62:63], v[66:67]
	ds_read_b128 v[134:137], v72 offset:34048
	v_add_f32_e32 v143, v66, v67
	s_waitcnt lgkmcnt(6)
; template <bool DUAL>
; __device__ __forceinline__ void rwkv_tile(const Params& p, int l, int tile, unsigned char* smem) {
;     ...
;       for (int i = 0; i < 32; ++i) {
;         const int inx = (i + 1) & 31;
;         const float4 nw4 = *(const float4*)(rp + inx * 384), nkk4 = *(const float4*)(rp + inx * 384 + 64), nkb4 = *(const float4*)(rp + inx * 384 + 128);
;         const float4 nkd4 = *(const float4*)(rp + inx * 384 + 192), nr4 = *(const float4*)(rp + inx * 384 + 256);
;         const float nv = vp[inx * 384];
;         v2f t = sA * (v2f){kk4.x, kk4.y};
;         t = sB * (v2f){kk4.z, kk4.w} + t;
;         float sa = t.x + t.y, ia = 0.f;
;         if (DUAL) {
;           v2f ti = iA * (v2f){kk4.x, kk4.y};
;           ti = iB * (v2f){kk4.z, kk4.w} + ti;
;           ia = ti.x + ti.y;
;           sa += dppf<0xB1>(sa); ia += dppf<0xB1>(ia);
;           sa += dppf<0x4E>(sa); ia += dppf<0x4E>(ia);
;           sa += dppf<0x141>(sa); ia += dppf<0x141>(ia);
;           sa += dppf<0x140>(sa); ia += dppf<0x140>(ia);
;         } else {
;           sa = sum16(sa);
;         }
;         v2f cA = sA * (v2f){w4.x, w4.y} + (v2f){kd4.x, kd4.y} * v;
;         v2f cB = sB * (v2f){w4.z, w4.w} + (v2f){kd4.z, kd4.w} * v;
;         sA = cA - (v2f){kb4.x, kb4.y} * sa;
;         sB = cB - (v2f){kb4.z, kb4.w} * sa;
;         v2f u = sA * (v2f){r4.x, r4.y};
;         u = sB * (v2f){r4.z, r4.w} + u;
;         float y = u.x + u.y, g = 0.f;
	v_pk_mul_f32 v[64:65], v[60:61], v[220:221]
	v_pk_fma_f32 v[64:65], v[62:63], v[222:223], v[64:65]
	v_add_f32_e32 v64, v64, v65
	v_pk_mul_f32 v[60:61], v[60:61], v[216:217]
	v_pk_mul_f32 v[62:63], v[62:63], v[218:219]
	v_add_f32_dpp v64, v64, v64 quad_perm:[1,0,3,2] row_mask:0xf bank_mask:0xf bound_ctrl:1
	v_pk_fma_f32 v[60:61], v[236:237], v[228:229], v[60:61] op_sel_hi:[0,1,1]
	v_pk_fma_f32 v[62:63], v[236:237], v[230:231], v[62:63] op_sel_hi:[0,1,1]
	v_add_f32_dpp v64, v64, v64 quad_perm:[2,3,0,1] row_mask:0xf bank_mask:0xf bound_ctrl:1
	ds_read_b128 v[220:223], v72 offset:34816
	ds_read_b128 v[216:219], v72 offset:34560
	v_add_f32_dpp v64, v64, v64 row_half_mirror row_mask:0xf bank_mask:0xf bound_ctrl:1
	ds_read_b128 v[228:231], v72 offset:35328
	ds_read_b32 v236, v73 offset:35840
	v_add_f32_dpp v64, v64, v64 row_mirror row_mask:0xf bank_mask:0xf bound_ctrl:1
	v_pk_fma_f32 v[60:61], v[224:225], v[64:65], v[60:61] op_sel_hi:[1,0,1] neg_lo:[1,0,0] neg_hi:[1,0,0]
	v_pk_fma_f32 v[62:63], v[226:227], v[64:65], v[62:63] op_sel_hi:[1,0,1] neg_lo:[1,0,0] neg_hi:[1,0,0]
	ds_read_b128 v[224:227], v72 offset:35072
	v_pk_mul_f32 v[66:67], v[232:233], v[60:61]
	v_pk_fma_f32 v[66:67], v[234:235], v[62:63], v[66:67]
	ds_read_b128 v[232:235], v72 offset:35584
	v_add_f32_e32 v144, v66, v67
	s_waitcnt lgkmcnt(6)
	v_pk_mul_f32 v[64:65], v[60:61], v[122:123]
	v_pk_fma_f32 v[64:65], v[62:63], v[124:125], v[64:65]
	v_add_f32_e32 v64, v64, v65
	v_pk_mul_f32 v[60:61], v[60:61], v[118:119]
	v_pk_mul_f32 v[62:63], v[62:63], v[120:121]
	v_add_f32_dpp v64, v64, v64 quad_perm:[1,0,3,2] row_mask:0xf bank_mask:0xf bound_ctrl:1
	v_pk_fma_f32 v[60:61], v[138:139], v[130:131], v[60:61] op_sel_hi:[0,1,1]
	v_pk_fma_f32 v[62:63], v[138:139], v[132:133], v[62:63] op_sel_hi:[0,1,1]
	v_add_f32_dpp v64, v64, v64 quad_perm:[2,3,0,1] row_mask:0xf bank_mask:0xf bound_ctrl:1
	ds_read_b128 v[122:125], v72 offset:36352
	ds_read_b128 v[118:121], v72 offset:36096
	v_add_f32_dpp v64, v64, v64 row_half_mirror row_mask:0xf bank_mask:0xf bound_ctrl:1
	ds_read_b128 v[130:133], v72 offset:36864
	ds_read_b32 v138, v73 offset:37376
	v_add_f32_dpp v64, v64, v64 row_mirror row_mask:0xf bank_mask:0xf bound_ctrl:1
	v_pk_fma_f32 v[60:61], v[126:127], v[64:65], v[60:61] op_sel_hi:[1,0,1] neg_lo:[1,0,0] neg_hi:[1,0,0]
	v_pk_fma_f32 v[62:63], v[128:129], v[64:65], v[62:63] op_sel_hi:[1,0,1] neg_lo:[1,0,0] neg_hi:[1,0,0]
	ds_read_b128 v[126:129], v72 offset:36608
	v_pk_mul_f32 v[66:67], v[134:135], v[60:61]
	v_pk_fma_f32 v[66:67], v[136:137], v[62:63], v[66:67]
	ds_read_b128 v[134:137], v72 offset:37120
	v_add_f32_e32 v145, v66, v67
	s_waitcnt lgkmcnt(6)
	v_pk_mul_f32 v[64:65], v[60:61], v[220:221]
	v_pk_fma_f32 v[64:65], v[62:63], v[222:223], v[64:65]
	v_add_f32_e32 v64, v64, v65
	v_pk_mul_f32 v[60:61], v[60:61], v[216:217]
	v_pk_mul_f32 v[62:63], v[62:63], v[218:219]
	v_add_f32_dpp v64, v64, v64 quad_perm:[1,0,3,2] row_mask:0xf bank_mask:0xf bound_ctrl:1
	v_pk_fma_f32 v[60:61], v[236:237], v[228:229], v[60:61] op_sel_hi:[0,1,1]
	v_pk_fma_f32 v[62:63], v[236:237], v[230:231], v[62:63] op_sel_hi:[0,1,1]
	v_add_f32_dpp v64, v64, v64 quad_perm:[2,3,0,1] row_mask:0xf bank_mask:0xf bound_ctrl:1
	ds_read_b128 v[220:223], v72 offset:37888
	ds_read_b128 v[216:219], v72 offset:37632
	v_add_f32_dpp v64, v64, v64 row_half_mirror row_mask:0xf bank_mask:0xf bound_ctrl:1
	ds_read_b128 v[228:231], v72 offset:38400
	ds_read_b32 v236, v73 offset:38912
	v_add_f32_dpp v64, v64, v64 row_mirror row_mask:0xf bank_mask:0xf bound_ctrl:1
	v_pk_fma_f32 v[60:61], v[224:225], v[64:65], v[60:61] op_sel_hi:[1,0,1] neg_lo:[1,0,0] neg_hi:[1,0,0]
	v_pk_fma_f32 v[62:63], v[226:227], v[64:65], v[62:63] op_sel_hi:[1,0,1] neg_lo:[1,0,0] neg_hi:[1,0,0]
	ds_read_b128 v[224:227], v72 offset:38144
	v_pk_mul_f32 v[66:67], v[232:233], v[60:61]
	v_pk_fma_f32 v[66:67], v[234:235], v[62:63], v[66:67]
	ds_read_b128 v[232:235], v72 offset:38656
	v_add_f32_e32 v146, v66, v67
	s_waitcnt lgkmcnt(6)
	v_pk_mul_f32 v[64:65], v[60:61], v[122:123]
	v_pk_fma_f32 v[64:65], v[62:63], v[124:125], v[64:65]
	v_add_f32_e32 v64, v64, v65
	v_pk_mul_f32 v[60:61], v[60:61], v[118:119]
	v_pk_mul_f32 v[62:63], v[62:63], v[120:121]
	v_add_f32_dpp v64, v64, v64 quad_perm:[1,0,3,2] row_mask:0xf bank_mask:0xf bound_ctrl:1
	v_pk_fma_f32 v[60:61], v[138:139], v[130:131], v[60:61] op_sel_hi:[0,1,1]
	v_pk_fma_f32 v[62:63], v[138:139], v[132:133], v[62:63] op_sel_hi:[0,1,1]
	v_add_f32_dpp v64, v64, v64 quad_perm:[2,3,0,1] row_mask:0xf bank_mask:0xf bound_ctrl:1
	ds_read_b128 v[122:125], v72 offset:39424
	ds_read_b128 v[118:121], v72 offset:39168
	v_add_f32_dpp v64, v64, v64 row_half_mirror row_mask:0xf bank_mask:0xf bound_ctrl:1
	ds_read_b128 v[130:133], v72 offset:39936
	ds_read_b32 v138, v73 offset:40448
	v_add_f32_dpp v64, v64, v64 row_mirror row_mask:0xf bank_mask:0xf bound_ctrl:1
	v_pk_fma_f32 v[60:61], v[126:127], v[64:65], v[60:61] op_sel_hi:[1,0,1] neg_lo:[1,0,0] neg_hi:[1,0,0]
	v_pk_fma_f32 v[62:63], v[128:129], v[64:65], v[62:63] op_sel_hi:[1,0,1] neg_lo:[1,0,0] neg_hi:[1,0,0]
	ds_read_b128 v[126:129], v72 offset:39680
	v_pk_mul_f32 v[66:67], v[134:135], v[60:61]
	v_pk_fma_f32 v[66:67], v[136:137], v[62:63], v[66:67]
	ds_read_b128 v[134:137], v72 offset:40192
	v_add_f32_e32 v147, v66, v67
	s_waitcnt lgkmcnt(6)
; template <bool DUAL>
; __device__ __forceinline__ void rwkv_tile(const Params& p, int l, int tile, unsigned char* smem) {
;     ...
;       for (int i = 0; i < 32; ++i) {
;         const int inx = (i + 1) & 31;
;         const float4 nw4 = *(const float4*)(rp + inx * 384), nkk4 = *(const float4*)(rp + inx * 384 + 64), nkb4 = *(const float4*)(rp + inx * 384 + 128);
;         const float4 nkd4 = *(const float4*)(rp + inx * 384 + 192), nr4 = *(const float4*)(rp + inx * 384 + 256);
;         const float nv = vp[inx * 384];
;         v2f t = sA * (v2f){kk4.x, kk4.y};
;         t = sB * (v2f){kk4.z, kk4.w} + t;
;         float sa = t.x + t.y, ia = 0.f;
;         if (DUAL) {
;           v2f ti = iA * (v2f){kk4.x, kk4.y};
;           ti = iB * (v2f){kk4.z, kk4.w} + ti;
;           ia = ti.x + ti.y;
;           sa += dppf<0xB1>(sa); ia += dppf<0xB1>(ia);
;           sa += dppf<0x4E>(sa); ia += dppf<0x4E>(ia);
;           sa += dppf<0x141>(sa); ia += dppf<0x141>(ia);
;           sa += dppf<0x140>(sa); ia += dppf<0x140>(ia);
;         } else {
;           sa = sum16(sa);
;         }
;         v2f cA = sA * (v2f){w4.x, w4.y} + (v2f){kd4.x, kd4.y} * v;
;         v2f cB = sB * (v2f){w4.z, w4.w} + (v2f){kd4.z, kd4.w} * v;
;         sA = cA - (v2f){kb4.x, kb4.y} * sa;
;         sB = cB - (v2f){kb4.z, kb4.w} * sa;
;         v2f u = sA * (v2f){r4.x, r4.y};
;         u = sB * (v2f){r4.z, r4.w} + u;
;         float y = u.x + u.y, g = 0.f;
	v_pk_mul_f32 v[64:65], v[60:61], v[220:221]
	v_pk_fma_f32 v[64:65], v[62:63], v[222:223], v[64:65]
	v_add_f32_e32 v64, v64, v65
	v_pk_mul_f32 v[60:61], v[60:61], v[216:217]
	v_pk_mul_f32 v[62:63], v[62:63], v[218:219]
	v_add_f32_dpp v64, v64, v64 quad_perm:[1,0,3,2] row_mask:0xf bank_mask:0xf bound_ctrl:1
	v_pk_fma_f32 v[60:61], v[236:237], v[228:229], v[60:61] op_sel_hi:[0,1,1]
	v_pk_fma_f32 v[62:63], v[236:237], v[230:231], v[62:63] op_sel_hi:[0,1,1]
	v_add_f32_dpp v64, v64, v64 quad_perm:[2,3,0,1] row_mask:0xf bank_mask:0xf bound_ctrl:1
	ds_read_b128 v[220:223], v72 offset:40960
	ds_read_b128 v[216:219], v72 offset:40704
	v_add_f32_dpp v64, v64, v64 row_half_mirror row_mask:0xf bank_mask:0xf bound_ctrl:1
	ds_read_b128 v[228:231], v72 offset:41472
	ds_read_b32 v236, v73 offset:41984
	v_add_f32_dpp v64, v64, v64 row_mirror row_mask:0xf bank_mask:0xf bound_ctrl:1
	v_pk_fma_f32 v[60:61], v[224:225], v[64:65], v[60:61] op_sel_hi:[1,0,1] neg_lo:[1,0,0] neg_hi:[1,0,0]
	v_pk_fma_f32 v[62:63], v[226:227], v[64:65], v[62:63] op_sel_hi:[1,0,1] neg_lo:[1,0,0] neg_hi:[1,0,0]
	ds_read_b128 v[224:227], v72 offset:41216
	v_pk_mul_f32 v[66:67], v[232:233], v[60:61]
	v_pk_fma_f32 v[66:67], v[234:235], v[62:63], v[66:67]
	ds_read_b128 v[232:235], v72 offset:41728
	v_add_f32_e32 v148, v66, v67
	s_waitcnt lgkmcnt(6)
	v_pk_mul_f32 v[64:65], v[60:61], v[122:123]
	v_pk_fma_f32 v[64:65], v[62:63], v[124:125], v[64:65]
	v_add_f32_e32 v64, v64, v65
	v_pk_mul_f32 v[60:61], v[60:61], v[118:119]
	v_pk_mul_f32 v[62:63], v[62:63], v[120:121]
	v_add_f32_dpp v64, v64, v64 quad_perm:[1,0,3,2] row_mask:0xf bank_mask:0xf bound_ctrl:1
	v_pk_fma_f32 v[60:61], v[138:139], v[130:131], v[60:61] op_sel_hi:[0,1,1]
	v_pk_fma_f32 v[62:63], v[138:139], v[132:133], v[62:63] op_sel_hi:[0,1,1]
	v_add_f32_dpp v64, v64, v64 quad_perm:[2,3,0,1] row_mask:0xf bank_mask:0xf bound_ctrl:1
	ds_read_b128 v[122:125], v72 offset:42496
	ds_read_b128 v[118:121], v72 offset:42240
	v_add_f32_dpp v64, v64, v64 row_half_mirror row_mask:0xf bank_mask:0xf bound_ctrl:1
	ds_read_b128 v[130:133], v72 offset:43008
	ds_read_b32 v138, v73 offset:43520
	v_add_f32_dpp v64, v64, v64 row_mirror row_mask:0xf bank_mask:0xf bound_ctrl:1
	v_pk_fma_f32 v[60:61], v[126:127], v[64:65], v[60:61] op_sel_hi:[1,0,1] neg_lo:[1,0,0] neg_hi:[1,0,0]
	v_pk_fma_f32 v[62:63], v[128:129], v[64:65], v[62:63] op_sel_hi:[1,0,1] neg_lo:[1,0,0] neg_hi:[1,0,0]
	ds_read_b128 v[126:129], v72 offset:42752
	v_pk_mul_f32 v[66:67], v[134:135], v[60:61]
	v_pk_fma_f32 v[66:67], v[136:137], v[62:63], v[66:67]
	ds_read_b128 v[134:137], v72 offset:43264
	v_add_f32_e32 v149, v66, v67
	s_waitcnt lgkmcnt(6)
	v_pk_mul_f32 v[64:65], v[60:61], v[220:221]
	v_pk_fma_f32 v[64:65], v[62:63], v[222:223], v[64:65]
	v_add_f32_e32 v64, v64, v65
	v_pk_mul_f32 v[60:61], v[60:61], v[216:217]
	v_pk_mul_f32 v[62:63], v[62:63], v[218:219]
	v_add_f32_dpp v64, v64, v64 quad_perm:[1,0,3,2] row_mask:0xf bank_mask:0xf bound_ctrl:1
	v_pk_fma_f32 v[60:61], v[236:237], v[228:229], v[60:61] op_sel_hi:[0,1,1]
	v_pk_fma_f32 v[62:63], v[236:237], v[230:231], v[62:63] op_sel_hi:[0,1,1]
	v_add_f32_dpp v64, v64, v64 quad_perm:[2,3,0,1] row_mask:0xf bank_mask:0xf bound_ctrl:1
	ds_read_b128 v[220:223], v72 offset:44032
	ds_read_b128 v[216:219], v72 offset:43776
	v_add_f32_dpp v64, v64, v64 row_half_mirror row_mask:0xf bank_mask:0xf bound_ctrl:1
	ds_read_b128 v[228:231], v72 offset:44544
	ds_read_b32 v236, v73 offset:45056
	v_add_f32_dpp v64, v64, v64 row_mirror row_mask:0xf bank_mask:0xf bound_ctrl:1
	v_pk_fma_f32 v[60:61], v[224:225], v[64:65], v[60:61] op_sel_hi:[1,0,1] neg_lo:[1,0,0] neg_hi:[1,0,0]
	v_pk_fma_f32 v[62:63], v[226:227], v[64:65], v[62:63] op_sel_hi:[1,0,1] neg_lo:[1,0,0] neg_hi:[1,0,0]
	ds_read_b128 v[224:227], v72 offset:44288
	v_pk_mul_f32 v[66:67], v[232:233], v[60:61]
	v_pk_fma_f32 v[66:67], v[234:235], v[62:63], v[66:67]
	ds_read_b128 v[232:235], v72 offset:44800
	v_add_f32_e32 v150, v66, v67
	s_waitcnt lgkmcnt(6)
	v_pk_mul_f32 v[64:65], v[60:61], v[122:123]
	v_pk_fma_f32 v[64:65], v[62:63], v[124:125], v[64:65]
	v_add_f32_e32 v64, v64, v65
	v_pk_mul_f32 v[60:61], v[60:61], v[118:119]
	v_pk_mul_f32 v[62:63], v[62:63], v[120:121]
	v_add_f32_dpp v64, v64, v64 quad_perm:[1,0,3,2] row_mask:0xf bank_mask:0xf bound_ctrl:1
	v_pk_fma_f32 v[60:61], v[138:139], v[130:131], v[60:61] op_sel_hi:[0,1,1]
	v_pk_fma_f32 v[62:63], v[138:139], v[132:133], v[62:63] op_sel_hi:[0,1,1]
	v_add_f32_dpp v64, v64, v64 quad_perm:[2,3,0,1] row_mask:0xf bank_mask:0xf bound_ctrl:1
	ds_read_b128 v[122:125], v72 offset:45568
	ds_read_b128 v[118:121], v72 offset:45312
	v_add_f32_dpp v64, v64, v64 row_half_mirror row_mask:0xf bank_mask:0xf bound_ctrl:1
	ds_read_b128 v[130:133], v72 offset:46080
	ds_read_b32 v138, v73 offset:46592
	v_add_f32_dpp v64, v64, v64 row_mirror row_mask:0xf bank_mask:0xf bound_ctrl:1
	v_pk_fma_f32 v[60:61], v[126:127], v[64:65], v[60:61] op_sel_hi:[1,0,1] neg_lo:[1,0,0] neg_hi:[1,0,0]
	v_pk_fma_f32 v[62:63], v[128:129], v[64:65], v[62:63] op_sel_hi:[1,0,1] neg_lo:[1,0,0] neg_hi:[1,0,0]
	ds_read_b128 v[126:129], v72 offset:45824
	v_pk_mul_f32 v[66:67], v[134:135], v[60:61]
	v_pk_fma_f32 v[66:67], v[136:137], v[62:63], v[66:67]
	ds_read_b128 v[134:137], v72 offset:46336
	v_add_f32_e32 v151, v66, v67
	s_waitcnt lgkmcnt(6)
; template <bool DUAL>
; __device__ __forceinline__ void rwkv_tile(const Params& p, int l, int tile, unsigned char* smem) {
;     ...
;       for (int i = 0; i < 32; ++i) {
;         const int inx = (i + 1) & 31;
;         const float4 nw4 = *(const float4*)(rp + inx * 384), nkk4 = *(const float4*)(rp + inx * 384 + 64), nkb4 = *(const float4*)(rp + inx * 384 + 128);
;         const float4 nkd4 = *(const float4*)(rp + inx * 384 + 192), nr4 = *(const float4*)(rp + inx * 384 + 256);
;         const float nv = vp[inx * 384];
;         v2f t = sA * (v2f){kk4.x, kk4.y};
;         t = sB * (v2f){kk4.z, kk4.w} + t;
;         float sa = t.x + t.y, ia = 0.f;
;         if (DUAL) {
;           v2f ti = iA * (v2f){kk4.x, kk4.y};
;           ti = iB * (v2f){kk4.z, kk4.w} + ti;
;           ia = ti.x + ti.y;
;           sa += dppf<0xB1>(sa); ia += dppf<0xB1>(ia);
;           sa += dppf<0x4E>(sa); ia += dppf<0x4E>(ia);
;           sa += dppf<0x141>(sa); ia += dppf<0x141>(ia);
;           sa += dppf<0x140>(sa); ia += dppf<0x140>(ia);
;         } else {
;           sa = sum16(sa);
;         }
;         v2f cA = sA * (v2f){w4.x, w4.y} + (v2f){kd4.x, kd4.y} * v;
;         v2f cB = sB * (v2f){w4.z, w4.w} + (v2f){kd4.z, kd4.w} * v;
;         sA = cA - (v2f){kb4.x, kb4.y} * sa;
;         sB = cB - (v2f){kb4.z, kb4.w} * sa;
;         v2f u = sA * (v2f){r4.x, r4.y};
;         u = sB * (v2f){r4.z, r4.w} + u;
;         float y = u.x + u.y, g = 0.f;
	v_pk_mul_f32 v[64:65], v[60:61], v[220:221]
	v_pk_fma_f32 v[64:65], v[62:63], v[222:223], v[64:65]
	v_add_f32_e32 v64, v64, v65
	v_pk_mul_f32 v[60:61], v[60:61], v[216:217]
	v_pk_mul_f32 v[62:63], v[62:63], v[218:219]
	v_add_f32_dpp v64, v64, v64 quad_perm:[1,0,3,2] row_mask:0xf bank_mask:0xf bound_ctrl:1
	v_pk_fma_f32 v[60:61], v[236:237], v[228:229], v[60:61] op_sel_hi:[0,1,1]
	v_pk_fma_f32 v[62:63], v[236:237], v[230:231], v[62:63] op_sel_hi:[0,1,1]
	v_add_f32_dpp v64, v64, v64 quad_perm:[2,3,0,1] row_mask:0xf bank_mask:0xf bound_ctrl:1
	ds_read_b128 v[220:223], v72 offset:47104
	ds_read_b128 v[216:219], v72 offset:46848
	v_add_f32_dpp v64, v64, v64 row_half_mirror row_mask:0xf bank_mask:0xf bound_ctrl:1
	ds_read_b128 v[228:231], v72 offset:47616
	ds_read_b32 v236, v73 offset:48128
	v_add_f32_dpp v64, v64, v64 row_mirror row_mask:0xf bank_mask:0xf bound_ctrl:1
	v_pk_fma_f32 v[60:61], v[224:225], v[64:65], v[60:61] op_sel_hi:[1,0,1] neg_lo:[1,0,0] neg_hi:[1,0,0]
	v_pk_fma_f32 v[62:63], v[226:227], v[64:65], v[62:63] op_sel_hi:[1,0,1] neg_lo:[1,0,0] neg_hi:[1,0,0]
	ds_read_b128 v[224:227], v72 offset:47360
	v_pk_mul_f32 v[66:67], v[232:233], v[60:61]
	v_pk_fma_f32 v[66:67], v[234:235], v[62:63], v[66:67]
	ds_read_b128 v[232:235], v72 offset:47872
	v_add_f32_e32 v152, v66, v67
	s_waitcnt lgkmcnt(6)
	v_pk_mul_f32 v[64:65], v[60:61], v[122:123]
	v_pk_fma_f32 v[64:65], v[62:63], v[124:125], v[64:65]
	v_add_f32_e32 v64, v64, v65
	v_pk_mul_f32 v[60:61], v[60:61], v[118:119]
	v_pk_mul_f32 v[62:63], v[62:63], v[120:121]
	v_add_f32_dpp v64, v64, v64 quad_perm:[1,0,3,2] row_mask:0xf bank_mask:0xf bound_ctrl:1
	v_pk_fma_f32 v[60:61], v[138:139], v[130:131], v[60:61] op_sel_hi:[0,1,1]
	v_pk_fma_f32 v[62:63], v[138:139], v[132:133], v[62:63] op_sel_hi:[0,1,1]
	v_add_f32_dpp v64, v64, v64 quad_perm:[2,3,0,1] row_mask:0xf bank_mask:0xf bound_ctrl:1
	ds_read_b128 v[122:125], v72 offset:48640
	ds_read_b128 v[118:121], v72 offset:48384
	v_add_f32_dpp v64, v64, v64 row_half_mirror row_mask:0xf bank_mask:0xf bound_ctrl:1
	ds_read_b128 v[130:133], v72 offset:49152
	ds_read_b32 v138, v73 offset:49664
	v_add_f32_dpp v64, v64, v64 row_mirror row_mask:0xf bank_mask:0xf bound_ctrl:1
	v_pk_fma_f32 v[60:61], v[126:127], v[64:65], v[60:61] op_sel_hi:[1,0,1] neg_lo:[1,0,0] neg_hi:[1,0,0]
	v_pk_fma_f32 v[62:63], v[128:129], v[64:65], v[62:63] op_sel_hi:[1,0,1] neg_lo:[1,0,0] neg_hi:[1,0,0]
	ds_read_b128 v[126:129], v72 offset:48896
	v_pk_mul_f32 v[66:67], v[134:135], v[60:61]
	v_pk_fma_f32 v[66:67], v[136:137], v[62:63], v[66:67]
	ds_read_b128 v[134:137], v72 offset:49408
	v_add_f32_e32 v153, v66, v67
	s_waitcnt lgkmcnt(6)
	v_pk_mul_f32 v[64:65], v[60:61], v[220:221]
	v_pk_fma_f32 v[64:65], v[62:63], v[222:223], v[64:65]
	v_add_f32_e32 v64, v64, v65
	v_pk_mul_f32 v[60:61], v[60:61], v[216:217]
	v_pk_mul_f32 v[62:63], v[62:63], v[218:219]
	v_add_f32_dpp v64, v64, v64 quad_perm:[1,0,3,2] row_mask:0xf bank_mask:0xf bound_ctrl:1
	v_pk_fma_f32 v[60:61], v[236:237], v[228:229], v[60:61] op_sel_hi:[0,1,1]
	v_pk_fma_f32 v[62:63], v[236:237], v[230:231], v[62:63] op_sel_hi:[0,1,1]
	v_add_f32_dpp v64, v64, v64 quad_perm:[2,3,0,1] row_mask:0xf bank_mask:0xf bound_ctrl:1
	ds_read_b128 v[220:223], v68 offset:25600
	ds_read_b128 v[216:219], v68 offset:25344
	v_add_f32_dpp v64, v64, v64 row_half_mirror row_mask:0xf bank_mask:0xf bound_ctrl:1
	ds_read_b128 v[228:231], v68 offset:26112
	ds_read_b32 v236, v69 offset:26624
	v_add_f32_dpp v64, v64, v64 row_mirror row_mask:0xf bank_mask:0xf bound_ctrl:1
	v_pk_fma_f32 v[60:61], v[224:225], v[64:65], v[60:61] op_sel_hi:[1,0,1] neg_lo:[1,0,0] neg_hi:[1,0,0]
	v_pk_fma_f32 v[62:63], v[226:227], v[64:65], v[62:63] op_sel_hi:[1,0,1] neg_lo:[1,0,0] neg_hi:[1,0,0]
	ds_read_b128 v[224:227], v68 offset:25856
	v_pk_mul_f32 v[66:67], v[232:233], v[60:61]
	v_pk_fma_f32 v[66:67], v[234:235], v[62:63], v[66:67]
	ds_read_b128 v[232:235], v68 offset:26368
	v_add_f32_e32 v154, v66, v67
	s_waitcnt lgkmcnt(6)
; __device__ __forceinline__ bf16_t f2bf(float f) { return (bf16_t)(pack2(f, 0.f) & 0xffffu); }
; template <bool DUAL>
; __device__ __forceinline__ void rwkv_tile(const Params& p, int l, int tile, unsigned char* smem) {
;     ...
;           y = sum16(y);
;         }
;         if (fr == (i & 15)) ykeep = y;
;         if ((i & 15) == 15) {
;           const int ii = (i & 16) + fr;
;           const int ri = (d == 0) ? ii + 1 : 32 - ii;
;           const int pi = plo - 1 + ri;
;           p.yR[((size_t)d * TOK + rowbase + pi) * 256 + h * 64 + row] = f2bf(ykeep);
;           if (DUAL) p.GID[((size_t)(d * 4 + b) * NSEG1 + (cix - CSPLIT) * 32 + ii) * 256 + h * 64 + row] = f2bf(gkeep);
	v_pk_mul_f32 v[64:65], v[60:61], v[122:123]
	v_pk_fma_f32 v[64:65], v[62:63], v[124:125], v[64:65]
	v_add_f32_e32 v64, v64, v65
	v_pk_mul_f32 v[60:61], v[60:61], v[118:119]
	v_pk_mul_f32 v[62:63], v[62:63], v[120:121]
	v_add_f32_dpp v64, v64, v64 quad_perm:[1,0,3,2] row_mask:0xf bank_mask:0xf bound_ctrl:1
	v_pk_fma_f32 v[60:61], v[138:139], v[130:131], v[60:61] op_sel_hi:[0,1,1]
	v_pk_fma_f32 v[62:63], v[138:139], v[132:133], v[62:63] op_sel_hi:[0,1,1]
	v_add_f32_dpp v64, v64, v64 quad_perm:[2,3,0,1] row_mask:0xf bank_mask:0xf bound_ctrl:1
	ds_read_b128 v[122:125], v68 offset:27136
	ds_read_b128 v[118:121], v68 offset:26880
	v_add_f32_dpp v64, v64, v64 row_half_mirror row_mask:0xf bank_mask:0xf bound_ctrl:1
	ds_read_b128 v[130:133], v68 offset:27648
	ds_read_b32 v138, v69 offset:28160
	v_add_f32_dpp v64, v64, v64 row_mirror row_mask:0xf bank_mask:0xf bound_ctrl:1
	v_pk_fma_f32 v[60:61], v[126:127], v[64:65], v[60:61] op_sel_hi:[1,0,1] neg_lo:[1,0,0] neg_hi:[1,0,0]
	v_pk_fma_f32 v[62:63], v[128:129], v[64:65], v[62:63] op_sel_hi:[1,0,1] neg_lo:[1,0,0] neg_hi:[1,0,0]
	ds_read_b128 v[126:129], v68 offset:27392
	v_pk_mul_f32 v[66:67], v[134:135], v[60:61]
	v_pk_fma_f32 v[66:67], v[136:137], v[62:63], v[66:67]
	ds_read_b128 v[134:137], v68 offset:27904
	v_add_f32_e32 v155, v66, v67
	v_add_f32_dpp v140, v140, v140 row_shl:8 row_mask:0xf bank_mask:0x3
	v_add_f32_dpp v140, v148, v148 row_shr:8 row_mask:0xf bank_mask:0xc
	v_add_f32_dpp v141, v141, v141 row_shl:8 row_mask:0xf bank_mask:0x3
	v_add_f32_dpp v141, v149, v149 row_shr:8 row_mask:0xf bank_mask:0xc
	v_add_f32_dpp v142, v142, v142 row_shl:8 row_mask:0xf bank_mask:0x3
	v_add_f32_dpp v142, v150, v150 row_shr:8 row_mask:0xf bank_mask:0xc
	v_add_f32_dpp v143, v143, v143 row_shl:8 row_mask:0xf bank_mask:0x3
	v_add_f32_dpp v143, v151, v151 row_shr:8 row_mask:0xf bank_mask:0xc
	v_add_f32_dpp v144, v144, v144 row_shl:8 row_mask:0xf bank_mask:0x3
	v_add_f32_dpp v144, v152, v152 row_shr:8 row_mask:0xf bank_mask:0xc
	v_add_f32_dpp v145, v145, v145 row_shl:8 row_mask:0xf bank_mask:0x3
	v_add_f32_dpp v145, v153, v153 row_shr:8 row_mask:0xf bank_mask:0xc
	v_add_f32_dpp v146, v146, v146 row_shl:8 row_mask:0xf bank_mask:0x3
	v_add_f32_dpp v146, v154, v154 row_shr:8 row_mask:0xf bank_mask:0xc
	v_add_f32_dpp v147, v147, v147 row_shl:8 row_mask:0xf bank_mask:0x3
	v_add_f32_dpp v147, v155, v155 row_shr:8 row_mask:0xf bank_mask:0xc
	v_add_f32_dpp v140, v140, v140 row_shl:4 row_mask:0xf bank_mask:0x5
	v_add_f32_dpp v140, v144, v144 row_shr:4 row_mask:0xf bank_mask:0xa
	v_add_f32_dpp v141, v141, v141 row_shl:4 row_mask:0xf bank_mask:0x5
	v_add_f32_dpp v141, v145, v145 row_shr:4 row_mask:0xf bank_mask:0xa
	v_add_f32_dpp v142, v142, v142 row_shl:4 row_mask:0xf bank_mask:0x5
	v_add_f32_dpp v142, v146, v146 row_shr:4 row_mask:0xf bank_mask:0xa
	v_add_f32_dpp v143, v143, v143 row_shl:4 row_mask:0xf bank_mask:0x5
	v_add_f32_dpp v143, v147, v147 row_shr:4 row_mask:0xf bank_mask:0xa
	v_cndmask_b32_e32 v156, v140, v142, vcc
	v_cndmask_b32_e32 v157, v142, v140, vcc
	v_cndmask_b32_e32 v159, v143, v141, vcc
	v_cndmask_b32_e32 v158, v141, v143, vcc
	v_add_f32_dpp v156, v157, v156 quad_perm:[2,3,0,1] row_mask:0xf bank_mask:0xf
	v_add_f32_dpp v158, v159, v158 quad_perm:[2,3,0,1] row_mask:0xf bank_mask:0xf
	v_cndmask_b32_e64 v160, v156, v158, s[58:59]
	v_cndmask_b32_e64 v161, v158, v156, s[58:59]
	v_add_u32_e32 v72, 0x6000, v72
	v_add_u32_e32 v73, 0x6000, v73
	v_add_f32_dpp v70, v161, v160 quad_perm:[1,0,3,2] row_mask:0xf bank_mask:0xf
	v_mov_b32_e32 v68, v99
	v_mov_b32_e32 v69, v100
	v_mov_b32_e32 v77, v71
	v_add_u32_e32 v75, 1, v77
	v_sub_u32_e32 v74, 32, v77
	v_cndmask_b32_e64 v74, v74, v75, s[36:37]
	v_add_u32_e32 v74, s28, v74
	v_ashrrev_i32_e32 v75, 31, v74
	v_lshl_add_u64 v[74:75], s[20:21], 0, v[74:75]
	v_lshlrev_b64 v[74:75], 9, v[74:75]
	v_cvt_pk_bf16_f32 v76, v70, v70
	v_lshl_add_u64 v[74:75], v[90:91], 0, v[74:75]
	global_store_short v[74:75], v76, off
	v_add_u32_e32 v71, 16, v71
	s_add_i32 s50, s50, 1
	s_cmp_lg_u32 s50, 1
	s_cbranch_scc1 .Lrw_nd_fin
	s_and_b64 s[54:55], s[42:43], s[54:55]
	s_and_saveexec_b64 s[68:69], s[54:55]
	s_cbranch_execz .Lrw_nd_middone
	s_waitcnt vmcnt(1)
	ds_write_b128 v101, v[32:35]
	ds_write_b128 v102, v[28:31]
	ds_write_b128 v103, v[36:39]
	s_and_saveexec_b64 s[54:55], s[44:45]
	ds_write_b128 v116, v[40:43]
	s_or_b64 exec, exec, s[54:55]
	ds_write_b128 v101, v[44:47] offset:13056
	ds_write_b128 v102, v[48:51] offset:13056
	ds_write_b128 v103, v[52:55] offset:13056
	s_mov_b64 s[54:55], exec
	s_and_b64 exec, exec, s[48:49]
	ds_write_b128 v116, v[56:59] offset:13056
	s_mov_b64 exec, s[54:55]
	s_add_i32 s57, s56, 1
	v_readlane_b32 s0, v254, 14
	s_cmp_ge_u32 s57, s0
	s_cbranch_scc1 .Lrw_nd_middone
	s_cmp_eq_u32 s57, 7
	s_cbranch_scc1 .Lrw_nd_middone
	s_cmp_eq_u32 s57, 8
	s_cbranch_scc1 .Lrw_nd_middone
	s_cmpk_eq_u32 s57, 0x87
	s_cbranch_scc1 .Lrw_nd_middone
	s_lshl_b32 s64, s57, 5
	s_sub_i32 s66, 0xe0, s64
	s_sub_i32 s0, 0x11e0, s64
	s_cmp_lt_u32 s57, 8
	s_cselect_b32 s66, s66, s0
	s_and_b64 s[0:1], s[36:37], exec
	s_cselect_b32 s57, s64, s66
	s_add_i32 s66, s57, -1
	v_add_u32_e32 v32, s66, v93
	v_lshlrev_b32_e32 v32, 11, v32
	v_mov_b32_e32 v33, v164
	v_lshl_add_u64 v[32:33], v[84:85], 0, v[32:33]
	global_load_dwordx4 v[32:35], v[32:33], off
	v_add_u32_e32 v28, s66, v94
	v_lshlrev_b32_e32 v28, 11, v28
	v_mov_b32_e32 v29, v164
	v_lshl_add_u64 v[28:29], v[84:85], 0, v[28:29]
	global_load_dwordx4 v[28:31], v[28:29], off
	v_add_u32_e32 v36, s66, v95
	v_lshlrev_b32_e32 v36, 11, v36
	v_mov_b32_e32 v37, v164
	v_lshl_add_u64 v[36:37], v[84:85], 0, v[36:37]
	global_load_dwordx4 v[36:39], v[36:37], off
	v_add_u32_e32 v44, s57, v93
	v_mov_b32_e32 v45, v164
	v_lshlrev_b64 v[44:45], 10, v[44:45]
	v_lshl_add_u64 v[44:45], v[86:87], 0, v[44:45]
	global_load_dwordx4 v[44:47], v[44:45], off
	v_add_u32_e32 v48, s57, v94
	v_mov_b32_e32 v49, v164
	v_lshlrev_b64 v[48:49], 10, v[48:49]
	v_lshl_add_u64 v[48:49], v[86:87], 0, v[48:49]
	global_load_dwordx4 v[48:51], v[48:49], off
	v_add_u32_e32 v52, s57, v95
	v_mov_b32_e32 v53, v164
	v_lshlrev_b64 v[52:53], 10, v[52:53]
	v_lshl_add_u64 v[52:53], v[86:87], 0, v[52:53]
	global_load_dwordx4 v[52:55], v[52:53], off
	s_or_b64 exec, exec, s[68:69]
	s_mov_b64 s[54:55], exec
	s_andn2_b64 exec, exec, s[46:47]
	v_add_u32_e32 v40, s66, v96
	v_lshlrev_b32_e32 v40, 11, v40
	v_mov_b32_e32 v41, v164
	v_lshl_add_u64 v[40:41], v[84:85], 0, v[40:41]
	global_load_dwordx4 v[40:43], v[40:41], off
	s_mov_b64 exec, s[54:55]
	s_and_b64 exec, exec, s[48:49]
	v_add_u32_e32 v56, s57, v96
	v_mov_b32_e32 v57, v164
	v_lshlrev_b64 v[56:57], 10, v[56:57]
	v_lshl_add_u64 v[56:57], v[86:87], 0, v[56:57]
	global_load_dwordx4 v[56:59], v[56:57], off
	s_mov_b64 exec, s[54:55]
	s_branch .Lrw_nd_loop

; template <bool DUAL>
; __device__ __forceinline__ void rwkv_tile(const Params& p, int l, int tile, unsigned char* smem) {
;     ...
;     __syncthreads();
;   }
.Lrw_nd_fin:
	s_branch .Lrw_nd_b2
	.section	.rodata,"a",@progbits
	.p2align	6, 0x0
